# micro1 plus: s_setprio 0 moved from before to after the barrier that closes each MFMA segment (the last MFMA is followed directly by s_barrier)
# baseline (speedup 1.0000x reference)
; #define PG8_STAGE(bufoff, gbase, voff) do { _Pragma("unroll") for (int _i = 0; _i < 2; ++_i) \
;         __builtin_amdgcn_global_load_lds((const unsigned*)((const char*)(gbase) + (voff)[_i]), (PG8_LAS unsigned*)(lds + (bufoff) + ldsw + _i * 8192), 16, 0, 0); } while (0)
; #define PG8_LDA(dst, b, h) do { _Pragma("unroll") for (int m = 0; m < 4; ++m) _Pragma("unroll") for (int k = 0; k < 2; ++k) dst[m][k] = *(const PG8_LAS bf16x8*)(lds + PG8_SA(b, h) + aoff + m * 2048 + k * 1024); } while (0)
; #define PG8_LDB(dst, b, h) do { _Pragma("unroll") for (int n = 0; n < 2; ++n) _Pragma("unroll") for (int k = 0; k < 2; ++k) dst[n][k] = *(const PG8_LAS bf16x8*)(lds + PG8_SB(b, h) + boff + n * 2048 + k * 1024); } while (0)
; #define PG8_MMA(ai, bj, At, Bt) do { __builtin_amdgcn_s_setprio(1); _Pragma("unroll") for (int m = 0; m < 4; ++m) _Pragma("unroll") for (int n = 0; n < 2; ++n) _Pragma("unroll") for (int k = 0; k < 2; ++k) \
;         acc[ai][bj][m][n] = __builtin_amdgcn_mfma_f32_16x16x32_bf16(Bt[n][k], At[m][k], acc[ai][bj][m][n], 0, 0, 0); __builtin_amdgcn_s_setprio(0); } while (0)
; #define PG8_WAIT_V(n) asm volatile("s_waitcnt vmcnt(" #n ")" ::: "memory")
; #define PG8_WAIT_L(n) asm volatile("s_waitcnt lgkmcnt(" #n ")" ::: "memory")
; #define PG8_BAR __builtin_amdgcn_s_barrier()
; #define PG8_SCHED __builtin_amdgcn_sched_barrier(0)
; template <class Epi, class Sched, bool ALIGN_EPI = false, bool SP2 = false>
; __device__ __forceinline__ void gemm_phase(PG8_LAS unsigned char* lds, const Gemm g, const Sched& S, const Epi& E) {
;     ...
;             PG8_LDB(B0, 0, 0); PG8_LDB(B1, 0, 1); PG8_SCHED; PG8_LDA(At, 0, 0); PG8_STAGE(PG8_SA(1, 1), a1 + hstep, voffA);
;             PG8_WAIT_V(8); PG8_WAIT_L(0); PG8_BAR; PG8_MMA(0, 0, At, B0); PG8_MMA(0, 1, At, B1); PG8_BAR; PG8_SCHED;
;             PG8_LDA(At, 0, 1); PG8_STAGE(PG8_SB(0, 0), b2, voffB); PG8_STAGE(PG8_SB(0, 1), b2 + hstep, voffB); PG8_STAGE(PG8_SA(0, 0), a2, voffA);
.LBB0_110:
	s_add_u32 s46, s44, 0xfffc0080
	s_addc_u32 s47, s45, -1
	s_add_i32 s67, 0, 0x10000
	s_cmp_eq_u32 s66, 12
	s_cselect_b32 s49, s17, s47
	s_cselect_b32 s48, s62, s46
	v_add_u32_e32 v145, s67, v143
	s_cselect_b32 s47, s15, s65
	s_cselect_b32 s46, s63, s64
	s_add_i32 s70, 0, 0x14000
	ds_read_b128 v[146:149], v145
	ds_read_b128 v[150:153], v145 offset:1024
	ds_read_b128 v[154:157], v145 offset:2048
	ds_read_b128 v[158:161], v145 offset:3072
	v_add_u32_e32 v145, s70, v143
	ds_read_b128 v[176:179], v145
	ds_read_b128 v[180:183], v145 offset:1024
	ds_read_b128 v[184:187], v145 offset:2048
	ds_read_b128 v[188:191], v145 offset:3072
	v_lshl_add_u64 v[200:201], s[44:45], 0, v[138:139]
	s_add_i32 m0, s50, 0xc000
	ds_read_b128 v[192:195], v144
	ds_read_b128 v[196:199], v144 offset:1024
	ds_read_b128 v[208:211], v144 offset:2048
	ds_read_b128 v[212:215], v144 offset:3072
	ds_read_b128 v[216:219], v144 offset:4096
	ds_read_b128 v[220:223], v144 offset:5120
	ds_read_b128 v[224:227], v144 offset:6144
	ds_read_b128 v[228:231], v144 offset:7168
	global_load_lds_dwordx4 v[200:201], off
	v_lshl_add_u64 v[200:201], s[44:45], 0, v[140:141]
	s_add_i32 m0, s50, 0xe000
	s_nop 0
	global_load_lds_dwordx4 v[200:201], off
	s_waitcnt vmcnt(8)
	s_waitcnt lgkmcnt(0)
	s_setprio 1
	s_barrier
	v_mfma_f32_16x16x32_bf16 v[126:129], v[146:149], v[192:195], v[126:129]
	v_mfma_f32_16x16x32_bf16 v[118:121], v[154:157], v[192:195], v[118:121]
	v_mfma_f32_16x16x32_bf16 v[110:113], v[146:149], v[208:211], v[110:113]
	v_mfma_f32_16x16x32_bf16 v[102:105], v[154:157], v[208:211], v[102:105]
	v_mfma_f32_16x16x32_bf16 v[94:97], v[146:149], v[216:219], v[94:97]
	v_mfma_f32_16x16x32_bf16 v[86:89], v[154:157], v[216:219], v[86:89]
	v_mfma_f32_16x16x32_bf16 v[76:79], v[146:149], v[224:227], v[76:79]
	v_mfma_f32_16x16x32_bf16 v[68:71], v[154:157], v[224:227], v[68:71]
	v_mfma_f32_16x16x32_bf16 v[126:129], v[150:153], v[196:199], v[126:129]
	v_mfma_f32_16x16x32_bf16 v[118:121], v[158:161], v[196:199], v[118:121]
	v_mfma_f32_16x16x32_bf16 v[110:113], v[150:153], v[212:215], v[110:113]
	v_mfma_f32_16x16x32_bf16 v[102:105], v[158:161], v[212:215], v[102:105]
	v_mfma_f32_16x16x32_bf16 v[94:97], v[150:153], v[220:223], v[94:97]
	v_mfma_f32_16x16x32_bf16 v[86:89], v[158:161], v[220:223], v[86:89]
	v_mfma_f32_16x16x32_bf16 v[76:79], v[150:153], v[228:231], v[76:79]
	v_mfma_f32_16x16x32_bf16 v[68:71], v[158:161], v[228:231], v[68:71]
	v_mfma_f32_16x16x32_bf16 v[122:125], v[176:179], v[192:195], v[122:125]
	v_mfma_f32_16x16x32_bf16 v[114:117], v[184:187], v[192:195], v[114:117]
	v_mfma_f32_16x16x32_bf16 v[106:109], v[176:179], v[208:211], v[106:109]
	v_mfma_f32_16x16x32_bf16 v[98:101], v[184:187], v[208:211], v[98:101]
	v_mfma_f32_16x16x32_bf16 v[90:93], v[176:179], v[216:219], v[90:93]
	v_mfma_f32_16x16x32_bf16 v[82:85], v[184:187], v[216:219], v[82:85]
	v_mfma_f32_16x16x32_bf16 v[72:75], v[176:179], v[224:227], v[72:75]
	v_mfma_f32_16x16x32_bf16 v[64:67], v[184:187], v[224:227], v[64:67]
	v_mfma_f32_16x16x32_bf16 v[122:125], v[180:183], v[196:199], v[122:125]
	v_mfma_f32_16x16x32_bf16 v[114:117], v[188:191], v[196:199], v[114:117]
	v_mfma_f32_16x16x32_bf16 v[106:109], v[180:183], v[212:215], v[106:109]
	v_mfma_f32_16x16x32_bf16 v[98:101], v[188:191], v[212:215], v[98:101]
	v_mfma_f32_16x16x32_bf16 v[90:93], v[180:183], v[220:223], v[90:93]
	v_mfma_f32_16x16x32_bf16 v[82:85], v[188:191], v[220:223], v[82:85]
	v_mfma_f32_16x16x32_bf16 v[72:75], v[180:183], v[228:231], v[72:75]
	v_mfma_f32_16x16x32_bf16 v[64:67], v[188:191], v[228:231], v[64:67]
	s_barrier
	s_setprio 0
	s_add_i32 s67, s67, s39
	v_lshl_add_u64 v[200:201], s[46:47], 0, v[134:135]
	s_mov_b32 m0, s67
	ds_read_b128 v[192:195], v144 offset:16384
	ds_read_b128 v[196:199], v144 offset:17408
	ds_read_b128 v[208:211], v144 offset:18432
	ds_read_b128 v[212:215], v144 offset:19456
	ds_read_b128 v[216:219], v144 offset:20480
	ds_read_b128 v[220:223], v144 offset:21504
	ds_read_b128 v[224:227], v144 offset:22528
	ds_read_b128 v[228:231], v144 offset:23552
	global_load_lds_dwordx4 v[200:201], off
	s_add_i32 m0, s67, 0x2000
	s_add_u32 s68, s46, 0x40000
	v_lshl_add_u64 v[232:233], s[46:47], 0, v[130:131]
	s_addc_u32 s69, s47, 0
	s_add_i32 s67, s70, s39
	global_load_lds_dwordx4 v[232:233], off
	v_lshl_add_u64 v[234:235], s[68:69], 0, v[134:135]
	s_mov_b32 m0, s67
	v_lshl_add_u64 v[236:237], s[48:49], 0, v[132:133]
	global_load_lds_dwordx4 v[234:235], off
	v_lshl_add_u64 v[234:235], s[68:69], 0, v[130:131]
	s_add_i32 m0, s67, 0x2000
	s_nop 0
	global_load_lds_dwordx4 v[234:235], off
	v_lshl_add_u64 v[234:235], s[48:49], 0, v[136:137]
	s_mov_b32 m0, s50
	s_nop 0
	global_load_lds_dwordx4 v[234:235], off
	s_mov_b32 m0, s51
	s_nop 0
	global_load_lds_dwordx4 v[236:237], off
	s_waitcnt vmcnt(8)
	s_waitcnt lgkmcnt(0)
	s_setprio 1
	s_barrier
; #define PG8_STAGE(bufoff, gbase, voff) do { _Pragma("unroll") for (int _i = 0; _i < 2; ++_i) \
;         __builtin_amdgcn_global_load_lds((const unsigned*)((const char*)(gbase) + (voff)[_i]), (PG8_LAS unsigned*)(lds + (bufoff) + ldsw + _i * 8192), 16, 0, 0); } while (0)
; #define PG8_LDA(dst, b, h) do { _Pragma("unroll") for (int m = 0; m < 4; ++m) _Pragma("unroll") for (int k = 0; k < 2; ++k) dst[m][k] = *(const PG8_LAS bf16x8*)(lds + PG8_SA(b, h) + aoff + m * 2048 + k * 1024); } while (0)
; #define PG8_LDB(dst, b, h) do { _Pragma("unroll") for (int n = 0; n < 2; ++n) _Pragma("unroll") for (int k = 0; k < 2; ++k) dst[n][k] = *(const PG8_LAS bf16x8*)(lds + PG8_SB(b, h) + boff + n * 2048 + k * 1024); } while (0)
; #define PG8_MMA(ai, bj, At, Bt) do { __builtin_amdgcn_s_setprio(1); _Pragma("unroll") for (int m = 0; m < 4; ++m) _Pragma("unroll") for (int n = 0; n < 2; ++n) _Pragma("unroll") for (int k = 0; k < 2; ++k) \
;         acc[ai][bj][m][n] = __builtin_amdgcn_mfma_f32_16x16x32_bf16(Bt[n][k], At[m][k], acc[ai][bj][m][n], 0, 0, 0); __builtin_amdgcn_s_setprio(0); } while (0)
; #define PG8_WAIT_V(n) asm volatile("s_waitcnt vmcnt(" #n ")" ::: "memory")
; #define PG8_WAIT_L(n) asm volatile("s_waitcnt lgkmcnt(" #n ")" ::: "memory")
; #define PG8_BAR __builtin_amdgcn_s_barrier()
; #define PG8_SCHED __builtin_amdgcn_sched_barrier(0)
; template <class Epi, class Sched, bool ALIGN_EPI = false, bool SP2 = false>
; __device__ __forceinline__ void gemm_phase(PG8_LAS unsigned char* lds, const Gemm g, const Sched& S, const Epi& E) {
;     ...
;             PG8_LDA(At, 0, 1); PG8_STAGE(PG8_SB(0, 0), b2, voffB); PG8_STAGE(PG8_SB(0, 1), b2 + hstep, voffB); PG8_STAGE(PG8_SA(0, 0), a2, voffA);
;             PG8_WAIT_V(8); PG8_WAIT_L(0); PG8_BAR; PG8_MMA(1, 0, At, B0); PG8_MMA(1, 1, At, B1); PG8_BAR; PG8_SCHED;
;             PG8_LDB(B0, 1, 0); PG8_LDB(B1, 1, 1); PG8_SCHED; PG8_LDA(At, 1, 0); PG8_STAGE(PG8_SA(0, 1), a2 + hstep, voffA);
;             PG8_WAIT_V(8); PG8_WAIT_L(0); PG8_BAR; PG8_MMA(0, 0, At, B0); PG8_MMA(0, 1, At, B1); PG8_BAR; PG8_SCHED;
	v_mfma_f32_16x16x32_bf16 v[60:63], v[146:149], v[192:195], v[60:63]
	v_mfma_f32_16x16x32_bf16 v[52:55], v[154:157], v[192:195], v[52:55]
	v_mfma_f32_16x16x32_bf16 v[44:47], v[146:149], v[208:211], v[44:47]
	v_mfma_f32_16x16x32_bf16 v[36:39], v[154:157], v[208:211], v[36:39]
	v_mfma_f32_16x16x32_bf16 v[28:31], v[146:149], v[216:219], v[28:31]
	v_mfma_f32_16x16x32_bf16 v[20:23], v[154:157], v[216:219], v[20:23]
	v_mfma_f32_16x16x32_bf16 v[12:15], v[146:149], v[224:227], v[12:15]
	v_mfma_f32_16x16x32_bf16 v[4:7], v[154:157], v[224:227], v[4:7]
	v_mfma_f32_16x16x32_bf16 v[60:63], v[150:153], v[196:199], v[60:63]
	v_mfma_f32_16x16x32_bf16 v[52:55], v[158:161], v[196:199], v[52:55]
	v_mfma_f32_16x16x32_bf16 v[44:47], v[150:153], v[212:215], v[44:47]
	v_mfma_f32_16x16x32_bf16 v[36:39], v[158:161], v[212:215], v[36:39]
	v_mfma_f32_16x16x32_bf16 v[28:31], v[150:153], v[220:223], v[28:31]
	v_mfma_f32_16x16x32_bf16 v[20:23], v[158:161], v[220:223], v[20:23]
	v_mfma_f32_16x16x32_bf16 v[12:15], v[150:153], v[228:231], v[12:15]
	v_mfma_f32_16x16x32_bf16 v[4:7], v[158:161], v[228:231], v[4:7]
	v_mfma_f32_16x16x32_bf16 v[56:59], v[176:179], v[192:195], v[56:59]
	v_mfma_f32_16x16x32_bf16 v[48:51], v[184:187], v[192:195], v[48:51]
	v_mfma_f32_16x16x32_bf16 v[40:43], v[176:179], v[208:211], v[40:43]
	v_mfma_f32_16x16x32_bf16 v[32:35], v[184:187], v[208:211], v[32:35]
	v_mfma_f32_16x16x32_bf16 v[24:27], v[176:179], v[216:219], v[24:27]
	v_mfma_f32_16x16x32_bf16 v[16:19], v[184:187], v[216:219], v[16:19]
	v_mfma_f32_16x16x32_bf16 v[8:11], v[176:179], v[224:227], v[8:11]
	v_mfma_f32_16x16x32_bf16 v[0:3], v[184:187], v[224:227], v[0:3]
	v_mfma_f32_16x16x32_bf16 v[56:59], v[180:183], v[196:199], v[56:59]
	v_mfma_f32_16x16x32_bf16 v[48:51], v[188:191], v[196:199], v[48:51]
	v_mfma_f32_16x16x32_bf16 v[40:43], v[180:183], v[212:215], v[40:43]
	v_mfma_f32_16x16x32_bf16 v[32:35], v[188:191], v[212:215], v[32:35]
	v_mfma_f32_16x16x32_bf16 v[24:27], v[180:183], v[220:223], v[24:27]
	v_mfma_f32_16x16x32_bf16 v[16:19], v[188:191], v[220:223], v[16:19]
	v_mfma_f32_16x16x32_bf16 v[8:11], v[180:183], v[228:231], v[8:11]
	v_mfma_f32_16x16x32_bf16 v[0:3], v[188:191], v[228:231], v[0:3]
	s_barrier
	s_setprio 0
	s_add_i32 s67, 0, 0x18000
	v_add_u32_e32 v145, s67, v143
	s_add_i32 s68, 0, 0x1c000
	ds_read_b128 v[146:149], v145
	ds_read_b128 v[150:153], v145 offset:1024
	ds_read_b128 v[154:157], v145 offset:2048
	ds_read_b128 v[158:161], v145 offset:3072
	v_add_u32_e32 v145, s68, v143
	ds_read_b128 v[176:179], v145
	ds_read_b128 v[180:183], v145 offset:1024
	ds_read_b128 v[184:187], v145 offset:2048
	ds_read_b128 v[188:191], v145 offset:3072
	s_add_u32 s48, s48, 0x40000
	s_addc_u32 s49, s49, 0
	s_mov_b32 m0, s52
	v_lshl_add_u64 v[238:239], s[48:49], 0, v[136:137]
	ds_read_b128 v[192:195], v144 offset:32768
	ds_read_b128 v[196:199], v144 offset:33792
	ds_read_b128 v[208:211], v144 offset:34816
	ds_read_b128 v[212:215], v144 offset:35840
	ds_read_b128 v[216:219], v144 offset:36864
	ds_read_b128 v[220:223], v144 offset:37888
	ds_read_b128 v[224:227], v144 offset:38912
	ds_read_b128 v[228:231], v144 offset:39936
	global_load_lds_dwordx4 v[238:239], off
	v_lshl_add_u64 v[238:239], s[48:49], 0, v[132:133]
	s_mov_b32 m0, s53
	s_nop 0
	global_load_lds_dwordx4 v[238:239], off
	s_waitcnt vmcnt(8)
	s_waitcnt lgkmcnt(0)
	s_setprio 1
	s_barrier
	v_mfma_f32_16x16x32_bf16 v[126:129], v[146:149], v[192:195], v[126:129]
	v_mfma_f32_16x16x32_bf16 v[118:121], v[154:157], v[192:195], v[118:121]
	v_mfma_f32_16x16x32_bf16 v[110:113], v[146:149], v[208:211], v[110:113]
	v_mfma_f32_16x16x32_bf16 v[102:105], v[154:157], v[208:211], v[102:105]
	v_mfma_f32_16x16x32_bf16 v[94:97], v[146:149], v[216:219], v[94:97]
	v_mfma_f32_16x16x32_bf16 v[86:89], v[154:157], v[216:219], v[86:89]
	v_mfma_f32_16x16x32_bf16 v[76:79], v[146:149], v[224:227], v[76:79]
	v_mfma_f32_16x16x32_bf16 v[68:71], v[154:157], v[224:227], v[68:71]
	v_mfma_f32_16x16x32_bf16 v[126:129], v[150:153], v[196:199], v[126:129]
	v_mfma_f32_16x16x32_bf16 v[118:121], v[158:161], v[196:199], v[118:121]
	v_mfma_f32_16x16x32_bf16 v[110:113], v[150:153], v[212:215], v[110:113]
	v_mfma_f32_16x16x32_bf16 v[102:105], v[158:161], v[212:215], v[102:105]
	v_mfma_f32_16x16x32_bf16 v[94:97], v[150:153], v[220:223], v[94:97]
	v_mfma_f32_16x16x32_bf16 v[86:89], v[158:161], v[220:223], v[86:89]
	v_mfma_f32_16x16x32_bf16 v[76:79], v[150:153], v[228:231], v[76:79]
	v_mfma_f32_16x16x32_bf16 v[68:71], v[158:161], v[228:231], v[68:71]
	v_mfma_f32_16x16x32_bf16 v[122:125], v[176:179], v[192:195], v[122:125]
	v_mfma_f32_16x16x32_bf16 v[114:117], v[184:187], v[192:195], v[114:117]
	v_mfma_f32_16x16x32_bf16 v[106:109], v[176:179], v[208:211], v[106:109]
	v_mfma_f32_16x16x32_bf16 v[98:101], v[184:187], v[208:211], v[98:101]
	v_mfma_f32_16x16x32_bf16 v[90:93], v[176:179], v[216:219], v[90:93]
	v_mfma_f32_16x16x32_bf16 v[82:85], v[184:187], v[216:219], v[82:85]
	v_mfma_f32_16x16x32_bf16 v[72:75], v[176:179], v[224:227], v[72:75]
	v_mfma_f32_16x16x32_bf16 v[64:67], v[184:187], v[224:227], v[64:67]
	v_mfma_f32_16x16x32_bf16 v[122:125], v[180:183], v[196:199], v[122:125]
	v_mfma_f32_16x16x32_bf16 v[114:117], v[188:191], v[196:199], v[114:117]
	v_mfma_f32_16x16x32_bf16 v[106:109], v[180:183], v[212:215], v[106:109]
	v_mfma_f32_16x16x32_bf16 v[98:101], v[188:191], v[212:215], v[98:101]
	v_mfma_f32_16x16x32_bf16 v[90:93], v[180:183], v[220:223], v[90:93]
	v_mfma_f32_16x16x32_bf16 v[82:85], v[188:191], v[220:223], v[82:85]
	v_mfma_f32_16x16x32_bf16 v[72:75], v[180:183], v[228:231], v[72:75]
	v_mfma_f32_16x16x32_bf16 v[64:67], v[188:191], v[228:231], v[64:67]
	s_barrier
; #define PG8_STAGE(bufoff, gbase, voff) do { _Pragma("unroll") for (int _i = 0; _i < 2; ++_i) \
;         __builtin_amdgcn_global_load_lds((const unsigned*)((const char*)(gbase) + (voff)[_i]), (PG8_LAS unsigned*)(lds + (bufoff) + ldsw + _i * 8192), 16, 0, 0); } while (0)
; #define PG8_LDA(dst, b, h) do { _Pragma("unroll") for (int m = 0; m < 4; ++m) _Pragma("unroll") for (int k = 0; k < 2; ++k) dst[m][k] = *(const PG8_LAS bf16x8*)(lds + PG8_SA(b, h) + aoff + m * 2048 + k * 1024); } while (0)
; #define PG8_MMA(ai, bj, At, Bt) do { __builtin_amdgcn_s_setprio(1); _Pragma("unroll") for (int m = 0; m < 4; ++m) _Pragma("unroll") for (int n = 0; n < 2; ++n) _Pragma("unroll") for (int k = 0; k < 2; ++k) \
;         acc[ai][bj][m][n] = __builtin_amdgcn_mfma_f32_16x16x32_bf16(Bt[n][k], At[m][k], acc[ai][bj][m][n], 0, 0, 0); __builtin_amdgcn_s_setprio(0); } while (0)
; #define PG8_WAIT_V(n) asm volatile("s_waitcnt vmcnt(" #n ")" ::: "memory")
; #define PG8_WAIT_L(n) asm volatile("s_waitcnt lgkmcnt(" #n ")" ::: "memory")
; #define PG8_BAR __builtin_amdgcn_s_barrier()
; #define PG8_SCHED __builtin_amdgcn_sched_barrier(0)
; template <class Epi, class Sched, bool ALIGN_EPI = false, bool SP2 = false>
; __device__ __forceinline__ void gemm_phase(PG8_LAS unsigned char* lds, const Gemm g, const Sched& S, const Epi& E) {
;     ...
;         for (int t = 0; t < nt; t += 2) {
;     ...
;             PG8_LDA(At, 1, 1); PG8_STAGE(PG8_SB(1, 0), b3, voffB); PG8_STAGE(PG8_SB(1, 1), b3 + hstep, voffB); PG8_STAGE(PG8_SA(1, 0), a3, voffA);
;             PG8_WAIT_V(8); PG8_WAIT_L(0); PG8_BAR; PG8_MMA(1, 0, At, B0); PG8_MMA(1, 1, At, B1); PG8_BAR; PG8_SCHED;
	s_setprio 0
	s_add_i32 s48, s67, s39
	v_lshl_add_u64 v[200:201], v[200:201], 0, s[40:41]
	s_mov_b32 m0, s48
	ds_read_b128 v[192:195], v144 offset:49152
	ds_read_b128 v[196:199], v144 offset:50176
	ds_read_b128 v[208:211], v144 offset:51200
	ds_read_b128 v[212:215], v144 offset:52224
	ds_read_b128 v[216:219], v144 offset:53248
	ds_read_b128 v[220:223], v144 offset:54272
	ds_read_b128 v[224:227], v144 offset:55296
	ds_read_b128 v[228:231], v144 offset:56320
	global_load_lds_dwordx4 v[200:201], off
	s_add_i32 m0, s48, 0x2000
	s_add_u32 s46, s46, 0x40080
	v_lshl_add_u64 v[200:201], v[232:233], 0, s[40:41]
	s_addc_u32 s47, s47, 0
	s_add_i32 s48, s68, s39
	global_load_lds_dwordx4 v[200:201], off
	v_lshl_add_u64 v[200:201], s[46:47], 0, v[134:135]
	s_mov_b32 m0, s48
	s_nop 0
	global_load_lds_dwordx4 v[200:201], off
	v_lshl_add_u64 v[200:201], s[46:47], 0, v[130:131]
	s_add_i32 m0, s48, 0x2000
	s_nop 0
	global_load_lds_dwordx4 v[200:201], off
	v_lshl_add_u64 v[200:201], v[234:235], 0, s[40:41]
	s_mov_b32 m0, s56
	s_nop 0
	global_load_lds_dwordx4 v[200:201], off
	v_lshl_add_u64 v[200:201], v[236:237], 0, s[40:41]
	s_mov_b32 m0, s57
	s_nop 0
	global_load_lds_dwordx4 v[200:201], off
	s_waitcnt vmcnt(8)
	s_waitcnt lgkmcnt(0)
	s_setprio 1
	s_barrier
	v_mfma_f32_16x16x32_bf16 v[60:63], v[146:149], v[192:195], v[60:63]
	v_mfma_f32_16x16x32_bf16 v[52:55], v[154:157], v[192:195], v[52:55]
	v_mfma_f32_16x16x32_bf16 v[44:47], v[146:149], v[208:211], v[44:47]
	v_mfma_f32_16x16x32_bf16 v[36:39], v[154:157], v[208:211], v[36:39]
	v_mfma_f32_16x16x32_bf16 v[28:31], v[146:149], v[216:219], v[28:31]
	v_mfma_f32_16x16x32_bf16 v[20:23], v[154:157], v[216:219], v[20:23]
	v_mfma_f32_16x16x32_bf16 v[12:15], v[146:149], v[224:227], v[12:15]
	v_mfma_f32_16x16x32_bf16 v[4:7], v[154:157], v[224:227], v[4:7]
	v_mfma_f32_16x16x32_bf16 v[60:63], v[150:153], v[196:199], v[60:63]
	v_mfma_f32_16x16x32_bf16 v[52:55], v[158:161], v[196:199], v[52:55]
	v_mfma_f32_16x16x32_bf16 v[44:47], v[150:153], v[212:215], v[44:47]
	v_mfma_f32_16x16x32_bf16 v[36:39], v[158:161], v[212:215], v[36:39]
	v_mfma_f32_16x16x32_bf16 v[28:31], v[150:153], v[220:223], v[28:31]
	v_mfma_f32_16x16x32_bf16 v[20:23], v[158:161], v[220:223], v[20:23]
	v_mfma_f32_16x16x32_bf16 v[12:15], v[150:153], v[228:231], v[12:15]
	v_mfma_f32_16x16x32_bf16 v[4:7], v[158:161], v[228:231], v[4:7]
	v_mfma_f32_16x16x32_bf16 v[56:59], v[176:179], v[192:195], v[56:59]
	v_mfma_f32_16x16x32_bf16 v[48:51], v[184:187], v[192:195], v[48:51]
	v_mfma_f32_16x16x32_bf16 v[40:43], v[176:179], v[208:211], v[40:43]
	v_mfma_f32_16x16x32_bf16 v[32:35], v[184:187], v[208:211], v[32:35]
	v_mfma_f32_16x16x32_bf16 v[24:27], v[176:179], v[216:219], v[24:27]
	v_mfma_f32_16x16x32_bf16 v[16:19], v[184:187], v[216:219], v[16:19]
	v_mfma_f32_16x16x32_bf16 v[8:11], v[176:179], v[224:227], v[8:11]
	v_mfma_f32_16x16x32_bf16 v[0:3], v[184:187], v[224:227], v[0:3]
	v_mfma_f32_16x16x32_bf16 v[56:59], v[180:183], v[196:199], v[56:59]
	v_mfma_f32_16x16x32_bf16 v[48:51], v[188:191], v[196:199], v[48:51]
	v_mfma_f32_16x16x32_bf16 v[40:43], v[180:183], v[212:215], v[40:43]
	v_mfma_f32_16x16x32_bf16 v[32:35], v[188:191], v[212:215], v[32:35]
	v_mfma_f32_16x16x32_bf16 v[24:27], v[180:183], v[220:223], v[24:27]
	v_mfma_f32_16x16x32_bf16 v[16:19], v[188:191], v[220:223], v[16:19]
	v_mfma_f32_16x16x32_bf16 v[8:11], v[180:183], v[228:231], v[8:11]
	v_mfma_f32_16x16x32_bf16 v[0:3], v[188:191], v[228:231], v[0:3]
	s_barrier
	s_setprio 0
	s_add_i32 s66, s66, 2
	s_add_u32 s44, s44, 0x100
	s_addc_u32 s45, s45, 0
	s_add_u32 s64, s64, 0x100
	s_addc_u32 s65, s65, 0
	s_cmp_gt_u32 s66, 13
	s_cbranch_scc0 .LBB0_110
	s_and_b64 vcc, exec, s[12:13]
	s_cbranch_vccz .LBB0_113
	s_barrier

; #define PG8_STAGE(bufoff, gbase, voff) do { _Pragma("unroll") for (int _i = 0; _i < 2; ++_i) \
;         __builtin_amdgcn_global_load_lds((const unsigned*)((const char*)(gbase) + (voff)[_i]), (PG8_LAS unsigned*)(lds + (bufoff) + ldsw + _i * 8192), 16, 0, 0); } while (0)
; #define PG8_LDA(dst, b, h) do { _Pragma("unroll") for (int m = 0; m < 4; ++m) _Pragma("unroll") for (int k = 0; k < 2; ++k) dst[m][k] = *(const PG8_LAS bf16x8*)(lds + PG8_SA(b, h) + aoff + m * 2048 + k * 1024); } while (0)
; #define PG8_LDB(dst, b, h) do { _Pragma("unroll") for (int n = 0; n < 2; ++n) _Pragma("unroll") for (int k = 0; k < 2; ++k) dst[n][k] = *(const PG8_LAS bf16x8*)(lds + PG8_SB(b, h) + boff + n * 2048 + k * 1024); } while (0)
; #define PG8_MMA(ai, bj, At, Bt) do { __builtin_amdgcn_s_setprio(1); _Pragma("unroll") for (int m = 0; m < 4; ++m) _Pragma("unroll") for (int n = 0; n < 2; ++n) _Pragma("unroll") for (int k = 0; k < 2; ++k) \
;         acc[ai][bj][m][n] = __builtin_amdgcn_mfma_f32_16x16x32_bf16(Bt[n][k], At[m][k], acc[ai][bj][m][n], 0, 0, 0); __builtin_amdgcn_s_setprio(0); } while (0)
; #define PG8_WAIT_V(n) asm volatile("s_waitcnt vmcnt(" #n ")" ::: "memory")
; #define PG8_WAIT_L(n) asm volatile("s_waitcnt lgkmcnt(" #n ")" ::: "memory")
; #define PG8_BAR __builtin_amdgcn_s_barrier()
; #define PG8_SCHED __builtin_amdgcn_sched_barrier(0)
; template <class Epi, class Sched, bool ALIGN_EPI = false, bool SP2 = false>
; __device__ __forceinline__ void gemm_phase(PG8_LAS unsigned char* lds, const Gemm g, const Sched& S, const Epi& E) {
;     ...
;             PG8_LDB(B0, 0, 0); PG8_LDB(B1, 0, 1); PG8_SCHED; PG8_LDA(At, 0, 0); PG8_STAGE(PG8_SA(1, 1), a1 + hstep, voffA);
;             PG8_WAIT_V(8); PG8_WAIT_L(0); PG8_BAR; PG8_MMA(0, 0, At, B0); PG8_MMA(0, 1, At, B1); PG8_BAR; PG8_SCHED;
;             PG8_LDA(At, 0, 1); PG8_STAGE(PG8_SB(0, 0), b2, voffB); PG8_STAGE(PG8_SB(0, 1), b2 + hstep, voffB); PG8_STAGE(PG8_SA(0, 0), a2, voffA);
.LBB0_129:
	s_add_u32 s48, s46, 0xfffc0080
	s_addc_u32 s49, s47, -1
	s_add_i32 s69, 0, 0x10000
	s_cmp_eq_u32 s68, 12
	s_cselect_b32 s51, s19, s49
	s_cselect_b32 s50, s64, s48
	v_add_u32_e32 v142, s69, v148
	s_cselect_b32 s49, s17, s67
	s_cselect_b32 s48, s65, s66
	s_add_i32 s72, 0, 0x14000
	ds_read_b128 v[150:153], v142
	ds_read_b128 v[154:157], v142 offset:1024
	ds_read_b128 v[158:161], v142 offset:2048
	ds_read_b128 v[176:179], v142 offset:3072
	v_add_u32_e32 v142, s72, v148
	ds_read_b128 v[180:183], v142
	ds_read_b128 v[184:187], v142 offset:1024
	ds_read_b128 v[188:191], v142 offset:2048
	ds_read_b128 v[192:195], v142 offset:3072
	v_lshl_add_u64 v[142:143], s[46:47], 0, v[138:139]
	s_add_i32 m0, s53, 0xc000
	ds_read_b128 v[196:199], v149
	ds_read_b128 v[208:211], v149 offset:1024
	ds_read_b128 v[212:215], v149 offset:2048
	ds_read_b128 v[216:219], v149 offset:3072
	ds_read_b128 v[220:223], v149 offset:4096
	ds_read_b128 v[224:227], v149 offset:5120
	ds_read_b128 v[228:231], v149 offset:6144
	ds_read_b128 v[232:235], v149 offset:7168
	global_load_lds_dwordx4 v[142:143], off
	v_lshl_add_u64 v[142:143], s[46:47], 0, v[140:141]
	s_add_i32 m0, s53, 0xe000
	s_nop 0
	global_load_lds_dwordx4 v[142:143], off
	s_waitcnt vmcnt(8)
	s_waitcnt lgkmcnt(0)
	s_setprio 1
	s_barrier
	v_mfma_f32_16x16x32_bf16 v[126:129], v[150:153], v[196:199], v[126:129]
	v_mfma_f32_16x16x32_bf16 v[122:125], v[158:161], v[196:199], v[122:125]
	v_mfma_f32_16x16x32_bf16 v[114:117], v[150:153], v[212:215], v[114:117]
	v_mfma_f32_16x16x32_bf16 v[106:109], v[158:161], v[212:215], v[106:109]
	v_mfma_f32_16x16x32_bf16 v[98:101], v[150:153], v[220:223], v[98:101]
	v_mfma_f32_16x16x32_bf16 v[90:93], v[158:161], v[220:223], v[90:93]
	v_mfma_f32_16x16x32_bf16 v[82:85], v[150:153], v[228:231], v[82:85]
	v_mfma_f32_16x16x32_bf16 v[72:75], v[158:161], v[228:231], v[72:75]
	v_mfma_f32_16x16x32_bf16 v[126:129], v[154:157], v[208:211], v[126:129]
	v_mfma_f32_16x16x32_bf16 v[122:125], v[176:179], v[208:211], v[122:125]
	v_mfma_f32_16x16x32_bf16 v[114:117], v[154:157], v[216:219], v[114:117]
	v_mfma_f32_16x16x32_bf16 v[106:109], v[176:179], v[216:219], v[106:109]
	v_mfma_f32_16x16x32_bf16 v[98:101], v[154:157], v[224:227], v[98:101]
	v_mfma_f32_16x16x32_bf16 v[90:93], v[176:179], v[224:227], v[90:93]
	v_mfma_f32_16x16x32_bf16 v[82:85], v[154:157], v[232:235], v[82:85]
	v_mfma_f32_16x16x32_bf16 v[72:75], v[176:179], v[232:235], v[72:75]
	v_mfma_f32_16x16x32_bf16 v[118:121], v[180:183], v[196:199], v[118:121]
	v_mfma_f32_16x16x32_bf16 v[110:113], v[188:191], v[196:199], v[110:113]
	v_mfma_f32_16x16x32_bf16 v[102:105], v[180:183], v[212:215], v[102:105]
	v_mfma_f32_16x16x32_bf16 v[94:97], v[188:191], v[212:215], v[94:97]
	v_mfma_f32_16x16x32_bf16 v[86:89], v[180:183], v[220:223], v[86:89]
	v_mfma_f32_16x16x32_bf16 v[76:79], v[188:191], v[220:223], v[76:79]
	v_mfma_f32_16x16x32_bf16 v[68:71], v[180:183], v[228:231], v[68:71]
	v_mfma_f32_16x16x32_bf16 v[64:67], v[188:191], v[228:231], v[64:67]
	v_mfma_f32_16x16x32_bf16 v[118:121], v[184:187], v[208:211], v[118:121]
	v_mfma_f32_16x16x32_bf16 v[110:113], v[192:195], v[208:211], v[110:113]
	v_mfma_f32_16x16x32_bf16 v[102:105], v[184:187], v[216:219], v[102:105]
	v_mfma_f32_16x16x32_bf16 v[94:97], v[192:195], v[216:219], v[94:97]
	v_mfma_f32_16x16x32_bf16 v[86:89], v[184:187], v[224:227], v[86:89]
	v_mfma_f32_16x16x32_bf16 v[76:79], v[192:195], v[224:227], v[76:79]
	v_mfma_f32_16x16x32_bf16 v[68:71], v[184:187], v[232:235], v[68:71]
	v_mfma_f32_16x16x32_bf16 v[64:67], v[192:195], v[232:235], v[64:67]
	s_barrier
	s_setprio 0
	s_add_i32 s69, s69, s52
	v_lshl_add_u64 v[142:143], s[48:49], 0, v[134:135]
	s_mov_b32 m0, s69
	ds_read_b128 v[196:199], v149 offset:16384
	ds_read_b128 v[208:211], v149 offset:17408
	ds_read_b128 v[212:215], v149 offset:18432
	ds_read_b128 v[216:219], v149 offset:19456
	ds_read_b128 v[220:223], v149 offset:20480
	ds_read_b128 v[224:227], v149 offset:21504
	ds_read_b128 v[228:231], v149 offset:22528
	ds_read_b128 v[232:235], v149 offset:23552
	global_load_lds_dwordx4 v[142:143], off
	s_add_i32 m0, s69, 0x2000
	s_add_u32 s70, s48, 0x40000
	v_lshl_add_u64 v[146:147], s[48:49], 0, v[130:131]
	s_addc_u32 s71, s49, 0
	s_add_i32 s69, s72, s52
	global_load_lds_dwordx4 v[146:147], off
	v_lshl_add_u64 v[200:201], s[70:71], 0, v[134:135]
	s_mov_b32 m0, s69
	v_lshl_add_u64 v[236:237], s[50:51], 0, v[132:133]
	global_load_lds_dwordx4 v[200:201], off
	v_lshl_add_u64 v[200:201], s[70:71], 0, v[130:131]
	s_add_i32 m0, s69, 0x2000
	s_nop 0
	global_load_lds_dwordx4 v[200:201], off
	v_lshl_add_u64 v[200:201], s[50:51], 0, v[136:137]
	s_mov_b32 m0, s53
	s_nop 0
	global_load_lds_dwordx4 v[200:201], off
	s_mov_b32 m0, s54
	s_nop 0
	global_load_lds_dwordx4 v[236:237], off
	s_waitcnt vmcnt(8)
	s_waitcnt lgkmcnt(0)
	s_setprio 1
	s_barrier
; #define PG8_STAGE(bufoff, gbase, voff) do { _Pragma("unroll") for (int _i = 0; _i < 2; ++_i) \
;         __builtin_amdgcn_global_load_lds((const unsigned*)((const char*)(gbase) + (voff)[_i]), (PG8_LAS unsigned*)(lds + (bufoff) + ldsw + _i * 8192), 16, 0, 0); } while (0)
; #define PG8_LDA(dst, b, h) do { _Pragma("unroll") for (int m = 0; m < 4; ++m) _Pragma("unroll") for (int k = 0; k < 2; ++k) dst[m][k] = *(const PG8_LAS bf16x8*)(lds + PG8_SA(b, h) + aoff + m * 2048 + k * 1024); } while (0)
; #define PG8_LDB(dst, b, h) do { _Pragma("unroll") for (int n = 0; n < 2; ++n) _Pragma("unroll") for (int k = 0; k < 2; ++k) dst[n][k] = *(const PG8_LAS bf16x8*)(lds + PG8_SB(b, h) + boff + n * 2048 + k * 1024); } while (0)
; #define PG8_MMA(ai, bj, At, Bt) do { __builtin_amdgcn_s_setprio(1); _Pragma("unroll") for (int m = 0; m < 4; ++m) _Pragma("unroll") for (int n = 0; n < 2; ++n) _Pragma("unroll") for (int k = 0; k < 2; ++k) \
;         acc[ai][bj][m][n] = __builtin_amdgcn_mfma_f32_16x16x32_bf16(Bt[n][k], At[m][k], acc[ai][bj][m][n], 0, 0, 0); __builtin_amdgcn_s_setprio(0); } while (0)
; #define PG8_WAIT_V(n) asm volatile("s_waitcnt vmcnt(" #n ")" ::: "memory")
; #define PG8_WAIT_L(n) asm volatile("s_waitcnt lgkmcnt(" #n ")" ::: "memory")
; #define PG8_BAR __builtin_amdgcn_s_barrier()
; #define PG8_SCHED __builtin_amdgcn_sched_barrier(0)
; template <class Epi, class Sched, bool ALIGN_EPI = false, bool SP2 = false>
; __device__ __forceinline__ void gemm_phase(PG8_LAS unsigned char* lds, const Gemm g, const Sched& S, const Epi& E) {
;     ...
;             PG8_LDA(At, 0, 1); PG8_STAGE(PG8_SB(0, 0), b2, voffB); PG8_STAGE(PG8_SB(0, 1), b2 + hstep, voffB); PG8_STAGE(PG8_SA(0, 0), a2, voffA);
;             PG8_WAIT_V(8); PG8_WAIT_L(0); PG8_BAR; PG8_MMA(1, 0, At, B0); PG8_MMA(1, 1, At, B1); PG8_BAR; PG8_SCHED;
;             PG8_LDB(B0, 1, 0); PG8_LDB(B1, 1, 1); PG8_SCHED; PG8_LDA(At, 1, 0); PG8_STAGE(PG8_SA(0, 1), a2 + hstep, voffA);
;             PG8_WAIT_V(8); PG8_WAIT_L(0); PG8_BAR; PG8_MMA(0, 0, At, B0); PG8_MMA(0, 1, At, B1); PG8_BAR; PG8_SCHED;
	v_mfma_f32_16x16x32_bf16 v[60:63], v[150:153], v[196:199], v[60:63]
	v_mfma_f32_16x16x32_bf16 v[56:59], v[158:161], v[196:199], v[56:59]
	v_mfma_f32_16x16x32_bf16 v[48:51], v[150:153], v[212:215], v[48:51]
	v_mfma_f32_16x16x32_bf16 v[40:43], v[158:161], v[212:215], v[40:43]
	v_mfma_f32_16x16x32_bf16 v[32:35], v[150:153], v[220:223], v[32:35]
	v_mfma_f32_16x16x32_bf16 v[24:27], v[158:161], v[220:223], v[24:27]
	v_mfma_f32_16x16x32_bf16 v[16:19], v[150:153], v[228:231], v[16:19]
	v_mfma_f32_16x16x32_bf16 v[8:11], v[158:161], v[228:231], v[8:11]
	v_mfma_f32_16x16x32_bf16 v[60:63], v[154:157], v[208:211], v[60:63]
	v_mfma_f32_16x16x32_bf16 v[56:59], v[176:179], v[208:211], v[56:59]
	v_mfma_f32_16x16x32_bf16 v[48:51], v[154:157], v[216:219], v[48:51]
	v_mfma_f32_16x16x32_bf16 v[40:43], v[176:179], v[216:219], v[40:43]
	v_mfma_f32_16x16x32_bf16 v[32:35], v[154:157], v[224:227], v[32:35]
	v_mfma_f32_16x16x32_bf16 v[24:27], v[176:179], v[224:227], v[24:27]
	v_mfma_f32_16x16x32_bf16 v[16:19], v[154:157], v[232:235], v[16:19]
	v_mfma_f32_16x16x32_bf16 v[8:11], v[176:179], v[232:235], v[8:11]
	v_mfma_f32_16x16x32_bf16 v[52:55], v[180:183], v[196:199], v[52:55]
	v_mfma_f32_16x16x32_bf16 v[44:47], v[188:191], v[196:199], v[44:47]
	v_mfma_f32_16x16x32_bf16 v[36:39], v[180:183], v[212:215], v[36:39]
	v_mfma_f32_16x16x32_bf16 v[28:31], v[188:191], v[212:215], v[28:31]
	v_mfma_f32_16x16x32_bf16 v[20:23], v[180:183], v[220:223], v[20:23]
	v_mfma_f32_16x16x32_bf16 v[12:15], v[188:191], v[220:223], v[12:15]
	v_mfma_f32_16x16x32_bf16 v[4:7], v[180:183], v[228:231], v[4:7]
	v_mfma_f32_16x16x32_bf16 v[0:3], v[188:191], v[228:231], v[0:3]
	v_mfma_f32_16x16x32_bf16 v[52:55], v[184:187], v[208:211], v[52:55]
	v_mfma_f32_16x16x32_bf16 v[44:47], v[192:195], v[208:211], v[44:47]
	v_mfma_f32_16x16x32_bf16 v[36:39], v[184:187], v[216:219], v[36:39]
	v_mfma_f32_16x16x32_bf16 v[28:31], v[192:195], v[216:219], v[28:31]
	v_mfma_f32_16x16x32_bf16 v[20:23], v[184:187], v[224:227], v[20:23]
	v_mfma_f32_16x16x32_bf16 v[12:15], v[192:195], v[224:227], v[12:15]
	v_mfma_f32_16x16x32_bf16 v[4:7], v[184:187], v[232:235], v[4:7]
	v_mfma_f32_16x16x32_bf16 v[0:3], v[192:195], v[232:235], v[0:3]
	s_barrier
	s_setprio 0
	s_add_i32 s69, 0, 0x18000
	v_add_u32_e32 v144, s69, v148
	s_add_i32 s70, 0, 0x1c000
	ds_read_b128 v[150:153], v144
	ds_read_b128 v[154:157], v144 offset:1024
	ds_read_b128 v[158:161], v144 offset:2048
	ds_read_b128 v[176:179], v144 offset:3072
	v_add_u32_e32 v144, s70, v148
	ds_read_b128 v[180:183], v144
	ds_read_b128 v[184:187], v144 offset:1024
	ds_read_b128 v[188:191], v144 offset:2048
	ds_read_b128 v[192:195], v144 offset:3072
	s_add_u32 s50, s50, 0x40000
	s_addc_u32 s51, s51, 0
	s_mov_b32 m0, s55
	v_lshl_add_u64 v[238:239], s[50:51], 0, v[136:137]
	ds_read_b128 v[196:199], v149 offset:32768
	ds_read_b128 v[208:211], v149 offset:33792
	ds_read_b128 v[212:215], v149 offset:34816
	ds_read_b128 v[216:219], v149 offset:35840
	ds_read_b128 v[220:223], v149 offset:36864
	ds_read_b128 v[224:227], v149 offset:37888
	ds_read_b128 v[228:231], v149 offset:38912
	ds_read_b128 v[232:235], v149 offset:39936
	global_load_lds_dwordx4 v[238:239], off
	v_lshl_add_u64 v[238:239], s[50:51], 0, v[132:133]
	s_mov_b32 m0, s56
	s_nop 0
	global_load_lds_dwordx4 v[238:239], off
	s_waitcnt vmcnt(8)
	s_waitcnt lgkmcnt(0)
	s_setprio 1
	s_barrier
	v_mfma_f32_16x16x32_bf16 v[126:129], v[150:153], v[196:199], v[126:129]
	v_mfma_f32_16x16x32_bf16 v[122:125], v[158:161], v[196:199], v[122:125]
	v_mfma_f32_16x16x32_bf16 v[114:117], v[150:153], v[212:215], v[114:117]
	v_mfma_f32_16x16x32_bf16 v[106:109], v[158:161], v[212:215], v[106:109]
	v_mfma_f32_16x16x32_bf16 v[98:101], v[150:153], v[220:223], v[98:101]
	v_mfma_f32_16x16x32_bf16 v[90:93], v[158:161], v[220:223], v[90:93]
	v_mfma_f32_16x16x32_bf16 v[82:85], v[150:153], v[228:231], v[82:85]
	v_mfma_f32_16x16x32_bf16 v[72:75], v[158:161], v[228:231], v[72:75]
	v_mfma_f32_16x16x32_bf16 v[126:129], v[154:157], v[208:211], v[126:129]
	v_mfma_f32_16x16x32_bf16 v[122:125], v[176:179], v[208:211], v[122:125]
	v_mfma_f32_16x16x32_bf16 v[114:117], v[154:157], v[216:219], v[114:117]
	v_mfma_f32_16x16x32_bf16 v[106:109], v[176:179], v[216:219], v[106:109]
	v_mfma_f32_16x16x32_bf16 v[98:101], v[154:157], v[224:227], v[98:101]
	v_mfma_f32_16x16x32_bf16 v[90:93], v[176:179], v[224:227], v[90:93]
	v_mfma_f32_16x16x32_bf16 v[82:85], v[154:157], v[232:235], v[82:85]
	v_mfma_f32_16x16x32_bf16 v[72:75], v[176:179], v[232:235], v[72:75]
	v_mfma_f32_16x16x32_bf16 v[118:121], v[180:183], v[196:199], v[118:121]
	v_mfma_f32_16x16x32_bf16 v[110:113], v[188:191], v[196:199], v[110:113]
	v_mfma_f32_16x16x32_bf16 v[102:105], v[180:183], v[212:215], v[102:105]
	v_mfma_f32_16x16x32_bf16 v[94:97], v[188:191], v[212:215], v[94:97]
	v_mfma_f32_16x16x32_bf16 v[86:89], v[180:183], v[220:223], v[86:89]
	v_mfma_f32_16x16x32_bf16 v[76:79], v[188:191], v[220:223], v[76:79]
	v_mfma_f32_16x16x32_bf16 v[68:71], v[180:183], v[228:231], v[68:71]
	v_mfma_f32_16x16x32_bf16 v[64:67], v[188:191], v[228:231], v[64:67]
	v_mfma_f32_16x16x32_bf16 v[118:121], v[184:187], v[208:211], v[118:121]
	v_mfma_f32_16x16x32_bf16 v[110:113], v[192:195], v[208:211], v[110:113]
	v_mfma_f32_16x16x32_bf16 v[102:105], v[184:187], v[216:219], v[102:105]
	v_mfma_f32_16x16x32_bf16 v[94:97], v[192:195], v[216:219], v[94:97]
	v_mfma_f32_16x16x32_bf16 v[86:89], v[184:187], v[224:227], v[86:89]
	v_mfma_f32_16x16x32_bf16 v[76:79], v[192:195], v[224:227], v[76:79]
	v_mfma_f32_16x16x32_bf16 v[68:71], v[184:187], v[232:235], v[68:71]
	v_mfma_f32_16x16x32_bf16 v[64:67], v[192:195], v[232:235], v[64:67]
	s_barrier
; #define PG8_STAGE(bufoff, gbase, voff) do { _Pragma("unroll") for (int _i = 0; _i < 2; ++_i) \
;         __builtin_amdgcn_global_load_lds((const unsigned*)((const char*)(gbase) + (voff)[_i]), (PG8_LAS unsigned*)(lds + (bufoff) + ldsw + _i * 8192), 16, 0, 0); } while (0)
; #define PG8_LDA(dst, b, h) do { _Pragma("unroll") for (int m = 0; m < 4; ++m) _Pragma("unroll") for (int k = 0; k < 2; ++k) dst[m][k] = *(const PG8_LAS bf16x8*)(lds + PG8_SA(b, h) + aoff + m * 2048 + k * 1024); } while (0)
; #define PG8_MMA(ai, bj, At, Bt) do { __builtin_amdgcn_s_setprio(1); _Pragma("unroll") for (int m = 0; m < 4; ++m) _Pragma("unroll") for (int n = 0; n < 2; ++n) _Pragma("unroll") for (int k = 0; k < 2; ++k) \
;         acc[ai][bj][m][n] = __builtin_amdgcn_mfma_f32_16x16x32_bf16(Bt[n][k], At[m][k], acc[ai][bj][m][n], 0, 0, 0); __builtin_amdgcn_s_setprio(0); } while (0)
; #define PG8_WAIT_V(n) asm volatile("s_waitcnt vmcnt(" #n ")" ::: "memory")
; #define PG8_WAIT_L(n) asm volatile("s_waitcnt lgkmcnt(" #n ")" ::: "memory")
; #define PG8_BAR __builtin_amdgcn_s_barrier()
; #define PG8_SCHED __builtin_amdgcn_sched_barrier(0)
; template <class Epi, class Sched, bool ALIGN_EPI = false, bool SP2 = false>
; __device__ __forceinline__ void gemm_phase(PG8_LAS unsigned char* lds, const Gemm g, const Sched& S, const Epi& E) {
;     ...
;         for (int t = 0; t < nt; t += 2) {
;     ...
;             PG8_LDA(At, 1, 1); PG8_STAGE(PG8_SB(1, 0), b3, voffB); PG8_STAGE(PG8_SB(1, 1), b3 + hstep, voffB); PG8_STAGE(PG8_SA(1, 0), a3, voffA);
;             PG8_WAIT_V(8); PG8_WAIT_L(0); PG8_BAR; PG8_MMA(1, 0, At, B0); PG8_MMA(1, 1, At, B1); PG8_BAR; PG8_SCHED;
	s_setprio 0
	s_add_i32 s50, s69, s52
	v_lshl_add_u64 v[142:143], v[142:143], 0, s[40:41]
	s_mov_b32 m0, s50
	ds_read_b128 v[196:199], v149 offset:49152
	ds_read_b128 v[208:211], v149 offset:50176
	ds_read_b128 v[212:215], v149 offset:51200
	ds_read_b128 v[216:219], v149 offset:52224
	ds_read_b128 v[220:223], v149 offset:53248
	ds_read_b128 v[224:227], v149 offset:54272
	ds_read_b128 v[228:231], v149 offset:55296
	ds_read_b128 v[232:235], v149 offset:56320
	global_load_lds_dwordx4 v[142:143], off
	s_add_i32 m0, s50, 0x2000
	s_add_u32 s48, s48, 0x40080
	v_lshl_add_u64 v[142:143], v[146:147], 0, s[40:41]
	s_addc_u32 s49, s49, 0
	s_add_i32 s50, s70, s52
	global_load_lds_dwordx4 v[142:143], off
	v_lshl_add_u64 v[142:143], s[48:49], 0, v[134:135]
	s_mov_b32 m0, s50
	s_nop 0
	global_load_lds_dwordx4 v[142:143], off
	v_lshl_add_u64 v[142:143], s[48:49], 0, v[130:131]
	s_add_i32 m0, s50, 0x2000
	s_nop 0
	global_load_lds_dwordx4 v[142:143], off
	v_lshl_add_u64 v[142:143], v[200:201], 0, s[40:41]
	s_mov_b32 m0, s59
	s_nop 0
	global_load_lds_dwordx4 v[142:143], off
	v_lshl_add_u64 v[142:143], v[236:237], 0, s[40:41]
	s_mov_b32 m0, s60
	s_nop 0
	global_load_lds_dwordx4 v[142:143], off
	s_waitcnt vmcnt(8)
	s_waitcnt lgkmcnt(0)
	s_setprio 1
	s_barrier
	v_mfma_f32_16x16x32_bf16 v[60:63], v[150:153], v[196:199], v[60:63]
	v_mfma_f32_16x16x32_bf16 v[56:59], v[158:161], v[196:199], v[56:59]
	v_mfma_f32_16x16x32_bf16 v[48:51], v[150:153], v[212:215], v[48:51]
	v_mfma_f32_16x16x32_bf16 v[40:43], v[158:161], v[212:215], v[40:43]
	v_mfma_f32_16x16x32_bf16 v[32:35], v[150:153], v[220:223], v[32:35]
	v_mfma_f32_16x16x32_bf16 v[24:27], v[158:161], v[220:223], v[24:27]
	v_mfma_f32_16x16x32_bf16 v[16:19], v[150:153], v[228:231], v[16:19]
	v_mfma_f32_16x16x32_bf16 v[8:11], v[158:161], v[228:231], v[8:11]
	v_mfma_f32_16x16x32_bf16 v[60:63], v[154:157], v[208:211], v[60:63]
	v_mfma_f32_16x16x32_bf16 v[56:59], v[176:179], v[208:211], v[56:59]
	v_mfma_f32_16x16x32_bf16 v[48:51], v[154:157], v[216:219], v[48:51]
	v_mfma_f32_16x16x32_bf16 v[40:43], v[176:179], v[216:219], v[40:43]
	v_mfma_f32_16x16x32_bf16 v[32:35], v[154:157], v[224:227], v[32:35]
	v_mfma_f32_16x16x32_bf16 v[24:27], v[176:179], v[224:227], v[24:27]
	v_mfma_f32_16x16x32_bf16 v[16:19], v[154:157], v[232:235], v[16:19]
	v_mfma_f32_16x16x32_bf16 v[8:11], v[176:179], v[232:235], v[8:11]
	v_mfma_f32_16x16x32_bf16 v[52:55], v[180:183], v[196:199], v[52:55]
	v_mfma_f32_16x16x32_bf16 v[44:47], v[188:191], v[196:199], v[44:47]
	v_mfma_f32_16x16x32_bf16 v[36:39], v[180:183], v[212:215], v[36:39]
	v_mfma_f32_16x16x32_bf16 v[28:31], v[188:191], v[212:215], v[28:31]
	v_mfma_f32_16x16x32_bf16 v[20:23], v[180:183], v[220:223], v[20:23]
	v_mfma_f32_16x16x32_bf16 v[12:15], v[188:191], v[220:223], v[12:15]
	v_mfma_f32_16x16x32_bf16 v[4:7], v[180:183], v[228:231], v[4:7]
	v_mfma_f32_16x16x32_bf16 v[0:3], v[188:191], v[228:231], v[0:3]
	v_mfma_f32_16x16x32_bf16 v[52:55], v[184:187], v[208:211], v[52:55]
	v_mfma_f32_16x16x32_bf16 v[44:47], v[192:195], v[208:211], v[44:47]
	v_mfma_f32_16x16x32_bf16 v[36:39], v[184:187], v[216:219], v[36:39]
	v_mfma_f32_16x16x32_bf16 v[28:31], v[192:195], v[216:219], v[28:31]
	v_mfma_f32_16x16x32_bf16 v[20:23], v[184:187], v[224:227], v[20:23]
	v_mfma_f32_16x16x32_bf16 v[12:15], v[192:195], v[224:227], v[12:15]
	v_mfma_f32_16x16x32_bf16 v[4:7], v[184:187], v[232:235], v[4:7]
	v_mfma_f32_16x16x32_bf16 v[0:3], v[192:195], v[232:235], v[0:3]
	s_barrier
	s_setprio 0
	s_add_i32 s68, s68, 2
	s_add_u32 s46, s46, 0x100
	s_addc_u32 s47, s47, 0
	s_add_u32 s66, s66, 0x100
	s_addc_u32 s67, s67, 0
	s_cmp_gt_u32 s68, 13
	s_cbranch_scc0 .LBB0_129
	s_and_b64 vcc, exec, s[14:15]
	s_cbranch_vccz .LBB0_132
	s_barrier

; #define PG8_STAGE(bufoff, gbase, voff) do { _Pragma("unroll") for (int _i = 0; _i < 2; ++_i) \
;         __builtin_amdgcn_global_load_lds((const unsigned*)((const char*)(gbase) + (voff)[_i]), (PG8_LAS unsigned*)(lds + (bufoff) + ldsw + _i * 8192), 16, 0, 0); } while (0)
; #define PG8_LDA(dst, b, h) do { _Pragma("unroll") for (int m = 0; m < 4; ++m) _Pragma("unroll") for (int k = 0; k < 2; ++k) dst[m][k] = *(const PG8_LAS bf16x8*)(lds + PG8_SA(b, h) + aoff + m * 2048 + k * 1024); } while (0)
; #define PG8_LDB(dst, b, h) do { _Pragma("unroll") for (int n = 0; n < 2; ++n) _Pragma("unroll") for (int k = 0; k < 2; ++k) dst[n][k] = *(const PG8_LAS bf16x8*)(lds + PG8_SB(b, h) + boff + n * 2048 + k * 1024); } while (0)
; #define PG8_MMA(ai, bj, At, Bt) do { __builtin_amdgcn_s_setprio(1); _Pragma("unroll") for (int m = 0; m < 4; ++m) _Pragma("unroll") for (int n = 0; n < 2; ++n) _Pragma("unroll") for (int k = 0; k < 2; ++k) \
;         acc[ai][bj][m][n] = __builtin_amdgcn_mfma_f32_16x16x32_bf16(Bt[n][k], At[m][k], acc[ai][bj][m][n], 0, 0, 0); __builtin_amdgcn_s_setprio(0); } while (0)
; #define PG8_WAIT_V(n) asm volatile("s_waitcnt vmcnt(" #n ")" ::: "memory")
; #define PG8_WAIT_L(n) asm volatile("s_waitcnt lgkmcnt(" #n ")" ::: "memory")
; #define PG8_BAR __builtin_amdgcn_s_barrier()
; #define PG8_SCHED __builtin_amdgcn_sched_barrier(0)
; template <class Epi, class Sched, bool ALIGN_EPI = false, bool SP2 = false>
; __device__ __forceinline__ void gemm_phase(PG8_LAS unsigned char* lds, const Gemm g, const Sched& S, const Epi& E) {
;     ...
;             PG8_LDB(B0, 0, 0); PG8_LDB(B1, 0, 1); PG8_SCHED; PG8_LDA(At, 0, 0); PG8_STAGE(PG8_SA(1, 1), a1 + hstep, voffA);
;             PG8_WAIT_V(8); PG8_WAIT_L(0); PG8_BAR; PG8_MMA(0, 0, At, B0); PG8_MMA(0, 1, At, B1); PG8_BAR; PG8_SCHED;
;             PG8_LDA(At, 0, 1); PG8_STAGE(PG8_SB(0, 0), b2, voffB); PG8_STAGE(PG8_SB(0, 1), b2 + hstep, voffB); PG8_STAGE(PG8_SA(0, 0), a2, voffA);
.LBB0_159:
	s_add_u32 s48, s6, 0xfffc0080
	s_addc_u32 s49, s7, -1
	s_add_i32 s71, 0, 0x10000
	s_cmp_eq_u32 s70, 12
	s_cselect_b32 s51, s5, s49
	s_cselect_b32 s50, s17, s48
	s_cselect_b32 s49, s19, s69
	s_cselect_b32 s48, s67, s68
	s_add_i32 s74, 0, 0x14000
	v_add_u32_e32 v142, s71, v199
	v_add_u32_e32 v158, s74, v199
	ds_read_b128 v[130:133], v142
	ds_read_b128 v[134:137], v142 offset:1024
	ds_read_b128 v[138:141], v142 offset:2048
	s_waitcnt lgkmcnt(0)
	ds_read_b128 v[142:145], v142 offset:3072
	ds_read_b128 v[146:149], v158
	ds_read_b128 v[150:153], v158 offset:1024
	ds_read_b128 v[154:157], v158 offset:2048
	ds_read_b128 v[158:161], v158 offset:3072
	v_lshl_add_u64 v[196:197], s[6:7], 0, v[184:185]
	s_add_i32 m0, s11, 0xc000
	ds_read_b128 v[188:191], v200
	ds_read_b128 v[192:195], v200 offset:1024
	ds_read_b128 v[208:211], v200 offset:2048
	ds_read_b128 v[212:215], v200 offset:3072
	ds_read_b128 v[216:219], v200 offset:4096
	ds_read_b128 v[220:223], v200 offset:5120
	ds_read_b128 v[224:227], v200 offset:6144
	ds_read_b128 v[228:231], v200 offset:7168
	global_load_lds_dwordx4 v[196:197], off
	v_lshl_add_u64 v[196:197], s[6:7], 0, v[186:187]
	s_add_i32 m0, s11, 0xe000
	s_nop 0
	global_load_lds_dwordx4 v[196:197], off
	s_waitcnt vmcnt(8)
	s_waitcnt lgkmcnt(0)
	s_setprio 1
	s_barrier
	v_mfma_f32_16x16x32_bf16 v[126:129], v[130:133], v[188:191], v[126:129]
	v_mfma_f32_16x16x32_bf16 v[122:125], v[138:141], v[188:191], v[122:125]
	v_mfma_f32_16x16x32_bf16 v[110:113], v[130:133], v[208:211], v[110:113]
	v_mfma_f32_16x16x32_bf16 v[106:109], v[138:141], v[208:211], v[106:109]
	v_mfma_f32_16x16x32_bf16 v[94:97], v[130:133], v[216:219], v[94:97]
	v_mfma_f32_16x16x32_bf16 v[90:93], v[138:141], v[216:219], v[90:93]
	v_mfma_f32_16x16x32_bf16 v[76:79], v[130:133], v[224:227], v[76:79]
	v_mfma_f32_16x16x32_bf16 v[72:75], v[138:141], v[224:227], v[72:75]
	v_mfma_f32_16x16x32_bf16 v[126:129], v[134:137], v[192:195], v[126:129]
	v_mfma_f32_16x16x32_bf16 v[122:125], v[142:145], v[192:195], v[122:125]
	v_mfma_f32_16x16x32_bf16 v[110:113], v[134:137], v[212:215], v[110:113]
	v_mfma_f32_16x16x32_bf16 v[106:109], v[142:145], v[212:215], v[106:109]
	v_mfma_f32_16x16x32_bf16 v[94:97], v[134:137], v[220:223], v[94:97]
	v_mfma_f32_16x16x32_bf16 v[90:93], v[142:145], v[220:223], v[90:93]
	v_mfma_f32_16x16x32_bf16 v[76:79], v[134:137], v[228:231], v[76:79]
	v_mfma_f32_16x16x32_bf16 v[72:75], v[142:145], v[228:231], v[72:75]
	v_mfma_f32_16x16x32_bf16 v[118:121], v[146:149], v[188:191], v[118:121]
	v_mfma_f32_16x16x32_bf16 v[114:117], v[154:157], v[188:191], v[114:117]
	v_mfma_f32_16x16x32_bf16 v[102:105], v[146:149], v[208:211], v[102:105]
	v_mfma_f32_16x16x32_bf16 v[98:101], v[154:157], v[208:211], v[98:101]
	v_mfma_f32_16x16x32_bf16 v[86:89], v[146:149], v[216:219], v[86:89]
	v_mfma_f32_16x16x32_bf16 v[82:85], v[154:157], v[216:219], v[82:85]
	v_mfma_f32_16x16x32_bf16 v[68:71], v[146:149], v[224:227], v[68:71]
	v_mfma_f32_16x16x32_bf16 v[64:67], v[154:157], v[224:227], v[64:67]
	v_mfma_f32_16x16x32_bf16 v[118:121], v[150:153], v[192:195], v[118:121]
	v_mfma_f32_16x16x32_bf16 v[114:117], v[158:161], v[192:195], v[114:117]
	v_mfma_f32_16x16x32_bf16 v[102:105], v[150:153], v[212:215], v[102:105]
	v_mfma_f32_16x16x32_bf16 v[98:101], v[158:161], v[212:215], v[98:101]
	v_mfma_f32_16x16x32_bf16 v[86:89], v[150:153], v[220:223], v[86:89]
	v_mfma_f32_16x16x32_bf16 v[82:85], v[158:161], v[220:223], v[82:85]
	v_mfma_f32_16x16x32_bf16 v[68:71], v[150:153], v[228:231], v[68:71]
	v_mfma_f32_16x16x32_bf16 v[64:67], v[158:161], v[228:231], v[64:67]
	s_barrier
	s_setprio 0
	s_add_i32 s71, s71, s54
	v_lshl_add_u64 v[196:197], s[48:49], 0, v[178:179]
	s_mov_b32 m0, s71
	ds_read_b128 v[188:191], v200 offset:16384
	ds_read_b128 v[192:195], v200 offset:17408
	ds_read_b128 v[208:211], v200 offset:18432
	ds_read_b128 v[212:215], v200 offset:19456
	ds_read_b128 v[216:219], v200 offset:20480
	ds_read_b128 v[220:223], v200 offset:21504
	ds_read_b128 v[224:227], v200 offset:22528
	ds_read_b128 v[228:231], v200 offset:23552
	global_load_lds_dwordx4 v[196:197], off
	s_add_i32 m0, s71, 0x2000
	s_add_u32 s72, s48, 0x40000
	v_lshl_add_u64 v[232:233], s[48:49], 0, v[182:183]
	s_addc_u32 s73, s49, 0
	s_add_i32 s71, s74, s54
	global_load_lds_dwordx4 v[232:233], off
	v_lshl_add_u64 v[234:235], s[72:73], 0, v[178:179]
	s_mov_b32 m0, s71
	v_lshl_add_u64 v[236:237], s[50:51], 0, v[180:181]
	global_load_lds_dwordx4 v[234:235], off
	v_lshl_add_u64 v[234:235], s[72:73], 0, v[182:183]
	s_add_i32 m0, s71, 0x2000
	s_nop 0
	global_load_lds_dwordx4 v[234:235], off
	v_lshl_add_u64 v[234:235], s[50:51], 0, v[176:177]
	s_mov_b32 m0, s11
	s_nop 0
	global_load_lds_dwordx4 v[234:235], off
	s_mov_b32 m0, s55
	s_nop 0
	global_load_lds_dwordx4 v[236:237], off
	s_waitcnt vmcnt(8)
	s_waitcnt lgkmcnt(0)
	s_setprio 1
	s_barrier
; #define PG8_STAGE(bufoff, gbase, voff) do { _Pragma("unroll") for (int _i = 0; _i < 2; ++_i) \
;         __builtin_amdgcn_global_load_lds((const unsigned*)((const char*)(gbase) + (voff)[_i]), (PG8_LAS unsigned*)(lds + (bufoff) + ldsw + _i * 8192), 16, 0, 0); } while (0)
; #define PG8_LDA(dst, b, h) do { _Pragma("unroll") for (int m = 0; m < 4; ++m) _Pragma("unroll") for (int k = 0; k < 2; ++k) dst[m][k] = *(const PG8_LAS bf16x8*)(lds + PG8_SA(b, h) + aoff + m * 2048 + k * 1024); } while (0)
; #define PG8_LDB(dst, b, h) do { _Pragma("unroll") for (int n = 0; n < 2; ++n) _Pragma("unroll") for (int k = 0; k < 2; ++k) dst[n][k] = *(const PG8_LAS bf16x8*)(lds + PG8_SB(b, h) + boff + n * 2048 + k * 1024); } while (0)
; #define PG8_MMA(ai, bj, At, Bt) do { __builtin_amdgcn_s_setprio(1); _Pragma("unroll") for (int m = 0; m < 4; ++m) _Pragma("unroll") for (int n = 0; n < 2; ++n) _Pragma("unroll") for (int k = 0; k < 2; ++k) \
;         acc[ai][bj][m][n] = __builtin_amdgcn_mfma_f32_16x16x32_bf16(Bt[n][k], At[m][k], acc[ai][bj][m][n], 0, 0, 0); __builtin_amdgcn_s_setprio(0); } while (0)
; #define PG8_WAIT_V(n) asm volatile("s_waitcnt vmcnt(" #n ")" ::: "memory")
; #define PG8_WAIT_L(n) asm volatile("s_waitcnt lgkmcnt(" #n ")" ::: "memory")
; #define PG8_BAR __builtin_amdgcn_s_barrier()
; #define PG8_SCHED __builtin_amdgcn_sched_barrier(0)
; template <class Epi, class Sched, bool ALIGN_EPI = false, bool SP2 = false>
; __device__ __forceinline__ void gemm_phase(PG8_LAS unsigned char* lds, const Gemm g, const Sched& S, const Epi& E) {
;     ...
;             PG8_LDA(At, 0, 1); PG8_STAGE(PG8_SB(0, 0), b2, voffB); PG8_STAGE(PG8_SB(0, 1), b2 + hstep, voffB); PG8_STAGE(PG8_SA(0, 0), a2, voffA);
;             PG8_WAIT_V(8); PG8_WAIT_L(0); PG8_BAR; PG8_MMA(1, 0, At, B0); PG8_MMA(1, 1, At, B1); PG8_BAR; PG8_SCHED;
;             PG8_LDB(B0, 1, 0); PG8_LDB(B1, 1, 1); PG8_SCHED; PG8_LDA(At, 1, 0); PG8_STAGE(PG8_SA(0, 1), a2 + hstep, voffA);
;             PG8_WAIT_V(8); PG8_WAIT_L(0); PG8_BAR; PG8_MMA(0, 0, At, B0); PG8_MMA(0, 1, At, B1); PG8_BAR; PG8_SCHED;
	v_mfma_f32_16x16x32_bf16 v[60:63], v[130:133], v[188:191], v[60:63]
	v_mfma_f32_16x16x32_bf16 v[56:59], v[138:141], v[188:191], v[56:59]
	v_mfma_f32_16x16x32_bf16 v[44:47], v[130:133], v[208:211], v[44:47]
	v_mfma_f32_16x16x32_bf16 v[40:43], v[138:141], v[208:211], v[40:43]
	v_mfma_f32_16x16x32_bf16 v[28:31], v[130:133], v[216:219], v[28:31]
	v_mfma_f32_16x16x32_bf16 v[24:27], v[138:141], v[216:219], v[24:27]
	v_mfma_f32_16x16x32_bf16 v[12:15], v[130:133], v[224:227], v[12:15]
	v_mfma_f32_16x16x32_bf16 v[8:11], v[138:141], v[224:227], v[8:11]
	v_mfma_f32_16x16x32_bf16 v[60:63], v[134:137], v[192:195], v[60:63]
	v_mfma_f32_16x16x32_bf16 v[56:59], v[142:145], v[192:195], v[56:59]
	v_mfma_f32_16x16x32_bf16 v[44:47], v[134:137], v[212:215], v[44:47]
	v_mfma_f32_16x16x32_bf16 v[40:43], v[142:145], v[212:215], v[40:43]
	v_mfma_f32_16x16x32_bf16 v[28:31], v[134:137], v[220:223], v[28:31]
	v_mfma_f32_16x16x32_bf16 v[24:27], v[142:145], v[220:223], v[24:27]
	v_mfma_f32_16x16x32_bf16 v[12:15], v[134:137], v[228:231], v[12:15]
	v_mfma_f32_16x16x32_bf16 v[8:11], v[142:145], v[228:231], v[8:11]
	v_mfma_f32_16x16x32_bf16 v[52:55], v[146:149], v[188:191], v[52:55]
	v_mfma_f32_16x16x32_bf16 v[48:51], v[154:157], v[188:191], v[48:51]
	v_mfma_f32_16x16x32_bf16 v[36:39], v[146:149], v[208:211], v[36:39]
	v_mfma_f32_16x16x32_bf16 v[32:35], v[154:157], v[208:211], v[32:35]
	v_mfma_f32_16x16x32_bf16 v[20:23], v[146:149], v[216:219], v[20:23]
	v_mfma_f32_16x16x32_bf16 v[16:19], v[154:157], v[216:219], v[16:19]
	v_mfma_f32_16x16x32_bf16 v[4:7], v[146:149], v[224:227], v[4:7]
	v_mfma_f32_16x16x32_bf16 v[0:3], v[154:157], v[224:227], v[0:3]
	v_mfma_f32_16x16x32_bf16 v[52:55], v[150:153], v[192:195], v[52:55]
	v_mfma_f32_16x16x32_bf16 v[48:51], v[158:161], v[192:195], v[48:51]
	v_mfma_f32_16x16x32_bf16 v[36:39], v[150:153], v[212:215], v[36:39]
	v_mfma_f32_16x16x32_bf16 v[32:35], v[158:161], v[212:215], v[32:35]
	v_mfma_f32_16x16x32_bf16 v[20:23], v[150:153], v[220:223], v[20:23]
	v_mfma_f32_16x16x32_bf16 v[16:19], v[158:161], v[220:223], v[16:19]
	v_mfma_f32_16x16x32_bf16 v[4:7], v[150:153], v[228:231], v[4:7]
	v_mfma_f32_16x16x32_bf16 v[0:3], v[158:161], v[228:231], v[0:3]
	s_barrier
	s_setprio 0
	s_add_i32 s71, 0, 0x18000
	s_add_i32 s72, 0, 0x1c000
	v_add_u32_e32 v142, s71, v199
	v_add_u32_e32 v158, s72, v199
	ds_read_b128 v[130:133], v142
	ds_read_b128 v[134:137], v142 offset:1024
	ds_read_b128 v[138:141], v142 offset:2048
	ds_read_b128 v[142:145], v142 offset:3072
	ds_read_b128 v[146:149], v158
	ds_read_b128 v[150:153], v158 offset:1024
	ds_read_b128 v[154:157], v158 offset:2048
	ds_read_b128 v[158:161], v158 offset:3072
	s_add_u32 s50, s50, 0x40000
	s_addc_u32 s51, s51, 0
	s_mov_b32 m0, s56
	v_lshl_add_u64 v[238:239], s[50:51], 0, v[176:177]
	ds_read_b128 v[188:191], v200 offset:32768
	ds_read_b128 v[192:195], v200 offset:33792
	ds_read_b128 v[208:211], v200 offset:34816
	ds_read_b128 v[212:215], v200 offset:35840
	ds_read_b128 v[216:219], v200 offset:36864
	ds_read_b128 v[220:223], v200 offset:37888
	ds_read_b128 v[224:227], v200 offset:38912
	ds_read_b128 v[228:231], v200 offset:39936
	global_load_lds_dwordx4 v[238:239], off
	v_lshl_add_u64 v[238:239], s[50:51], 0, v[180:181]
	s_mov_b32 m0, s57
	s_nop 0
	global_load_lds_dwordx4 v[238:239], off
	s_waitcnt vmcnt(8)
	s_waitcnt lgkmcnt(0)
	s_setprio 1
	s_barrier
	v_mfma_f32_16x16x32_bf16 v[126:129], v[130:133], v[188:191], v[126:129]
	v_mfma_f32_16x16x32_bf16 v[122:125], v[138:141], v[188:191], v[122:125]
	v_mfma_f32_16x16x32_bf16 v[110:113], v[130:133], v[208:211], v[110:113]
	v_mfma_f32_16x16x32_bf16 v[106:109], v[138:141], v[208:211], v[106:109]
	v_mfma_f32_16x16x32_bf16 v[94:97], v[130:133], v[216:219], v[94:97]
	v_mfma_f32_16x16x32_bf16 v[90:93], v[138:141], v[216:219], v[90:93]
	v_mfma_f32_16x16x32_bf16 v[76:79], v[130:133], v[224:227], v[76:79]
	v_mfma_f32_16x16x32_bf16 v[72:75], v[138:141], v[224:227], v[72:75]
	v_mfma_f32_16x16x32_bf16 v[126:129], v[134:137], v[192:195], v[126:129]
	v_mfma_f32_16x16x32_bf16 v[122:125], v[142:145], v[192:195], v[122:125]
	v_mfma_f32_16x16x32_bf16 v[110:113], v[134:137], v[212:215], v[110:113]
	v_mfma_f32_16x16x32_bf16 v[106:109], v[142:145], v[212:215], v[106:109]
	v_mfma_f32_16x16x32_bf16 v[94:97], v[134:137], v[220:223], v[94:97]
	v_mfma_f32_16x16x32_bf16 v[90:93], v[142:145], v[220:223], v[90:93]
	v_mfma_f32_16x16x32_bf16 v[76:79], v[134:137], v[228:231], v[76:79]
	v_mfma_f32_16x16x32_bf16 v[72:75], v[142:145], v[228:231], v[72:75]
	v_mfma_f32_16x16x32_bf16 v[118:121], v[146:149], v[188:191], v[118:121]
	v_mfma_f32_16x16x32_bf16 v[114:117], v[154:157], v[188:191], v[114:117]
	v_mfma_f32_16x16x32_bf16 v[102:105], v[146:149], v[208:211], v[102:105]
	v_mfma_f32_16x16x32_bf16 v[98:101], v[154:157], v[208:211], v[98:101]
	v_mfma_f32_16x16x32_bf16 v[86:89], v[146:149], v[216:219], v[86:89]
	v_mfma_f32_16x16x32_bf16 v[82:85], v[154:157], v[216:219], v[82:85]
	v_mfma_f32_16x16x32_bf16 v[68:71], v[146:149], v[224:227], v[68:71]
	v_mfma_f32_16x16x32_bf16 v[64:67], v[154:157], v[224:227], v[64:67]
	v_mfma_f32_16x16x32_bf16 v[118:121], v[150:153], v[192:195], v[118:121]
	v_mfma_f32_16x16x32_bf16 v[114:117], v[158:161], v[192:195], v[114:117]
	v_mfma_f32_16x16x32_bf16 v[102:105], v[150:153], v[212:215], v[102:105]
	v_mfma_f32_16x16x32_bf16 v[98:101], v[158:161], v[212:215], v[98:101]
	v_mfma_f32_16x16x32_bf16 v[86:89], v[150:153], v[220:223], v[86:89]
	v_mfma_f32_16x16x32_bf16 v[82:85], v[158:161], v[220:223], v[82:85]
	v_mfma_f32_16x16x32_bf16 v[68:71], v[150:153], v[228:231], v[68:71]
	v_mfma_f32_16x16x32_bf16 v[64:67], v[158:161], v[228:231], v[64:67]
	s_barrier
; #define PG8_STAGE(bufoff, gbase, voff) do { _Pragma("unroll") for (int _i = 0; _i < 2; ++_i) \
;         __builtin_amdgcn_global_load_lds((const unsigned*)((const char*)(gbase) + (voff)[_i]), (PG8_LAS unsigned*)(lds + (bufoff) + ldsw + _i * 8192), 16, 0, 0); } while (0)
; #define PG8_LDA(dst, b, h) do { _Pragma("unroll") for (int m = 0; m < 4; ++m) _Pragma("unroll") for (int k = 0; k < 2; ++k) dst[m][k] = *(const PG8_LAS bf16x8*)(lds + PG8_SA(b, h) + aoff + m * 2048 + k * 1024); } while (0)
; #define PG8_MMA(ai, bj, At, Bt) do { __builtin_amdgcn_s_setprio(1); _Pragma("unroll") for (int m = 0; m < 4; ++m) _Pragma("unroll") for (int n = 0; n < 2; ++n) _Pragma("unroll") for (int k = 0; k < 2; ++k) \
;         acc[ai][bj][m][n] = __builtin_amdgcn_mfma_f32_16x16x32_bf16(Bt[n][k], At[m][k], acc[ai][bj][m][n], 0, 0, 0); __builtin_amdgcn_s_setprio(0); } while (0)
; #define PG8_WAIT_V(n) asm volatile("s_waitcnt vmcnt(" #n ")" ::: "memory")
; #define PG8_WAIT_L(n) asm volatile("s_waitcnt lgkmcnt(" #n ")" ::: "memory")
; #define PG8_BAR __builtin_amdgcn_s_barrier()
; #define PG8_SCHED __builtin_amdgcn_sched_barrier(0)
; template <class Epi, class Sched, bool ALIGN_EPI = false, bool SP2 = false>
; __device__ __forceinline__ void gemm_phase(PG8_LAS unsigned char* lds, const Gemm g, const Sched& S, const Epi& E) {
;     ...
;         for (int t = 0; t < nt; t += 2) {
;     ...
;             PG8_LDA(At, 1, 1); PG8_STAGE(PG8_SB(1, 0), b3, voffB); PG8_STAGE(PG8_SB(1, 1), b3 + hstep, voffB); PG8_STAGE(PG8_SA(1, 0), a3, voffA);
;             PG8_WAIT_V(8); PG8_WAIT_L(0); PG8_BAR; PG8_MMA(1, 0, At, B0); PG8_MMA(1, 1, At, B1); PG8_BAR; PG8_SCHED;
	s_setprio 0
	s_add_i32 s50, s71, s54
	v_lshl_add_u64 v[196:197], v[196:197], 0, s[40:41]
	s_mov_b32 m0, s50
	ds_read_b128 v[188:191], v200 offset:49152
	ds_read_b128 v[192:195], v200 offset:50176
	ds_read_b128 v[208:211], v200 offset:51200
	ds_read_b128 v[212:215], v200 offset:52224
	ds_read_b128 v[216:219], v200 offset:53248
	ds_read_b128 v[220:223], v200 offset:54272
	ds_read_b128 v[224:227], v200 offset:55296
	ds_read_b128 v[228:231], v200 offset:56320
	global_load_lds_dwordx4 v[196:197], off
	s_add_i32 m0, s50, 0x2000
	s_add_u32 s48, s48, 0x40080
	v_lshl_add_u64 v[196:197], v[232:233], 0, s[40:41]
	s_addc_u32 s49, s49, 0
	s_add_i32 s50, s72, s54
	global_load_lds_dwordx4 v[196:197], off
	v_lshl_add_u64 v[196:197], s[48:49], 0, v[178:179]
	s_mov_b32 m0, s50
	s_nop 0
	global_load_lds_dwordx4 v[196:197], off
	v_lshl_add_u64 v[196:197], s[48:49], 0, v[182:183]
	s_add_i32 m0, s50, 0x2000
	s_nop 0
	global_load_lds_dwordx4 v[196:197], off
	v_lshl_add_u64 v[196:197], v[234:235], 0, s[40:41]
	s_mov_b32 m0, s61
	s_nop 0
	global_load_lds_dwordx4 v[196:197], off
	v_lshl_add_u64 v[196:197], v[236:237], 0, s[40:41]
	s_mov_b32 m0, s62
	s_nop 0
	global_load_lds_dwordx4 v[196:197], off
	s_waitcnt vmcnt(8)
	s_waitcnt lgkmcnt(0)
	s_setprio 1
	s_barrier
	v_mfma_f32_16x16x32_bf16 v[60:63], v[130:133], v[188:191], v[60:63]
	v_mfma_f32_16x16x32_bf16 v[56:59], v[138:141], v[188:191], v[56:59]
	v_mfma_f32_16x16x32_bf16 v[44:47], v[130:133], v[208:211], v[44:47]
	v_mfma_f32_16x16x32_bf16 v[40:43], v[138:141], v[208:211], v[40:43]
	v_mfma_f32_16x16x32_bf16 v[28:31], v[130:133], v[216:219], v[28:31]
	v_mfma_f32_16x16x32_bf16 v[24:27], v[138:141], v[216:219], v[24:27]
	v_mfma_f32_16x16x32_bf16 v[12:15], v[130:133], v[224:227], v[12:15]
	v_mfma_f32_16x16x32_bf16 v[8:11], v[138:141], v[224:227], v[8:11]
	v_mfma_f32_16x16x32_bf16 v[60:63], v[134:137], v[192:195], v[60:63]
	v_mfma_f32_16x16x32_bf16 v[56:59], v[142:145], v[192:195], v[56:59]
	v_mfma_f32_16x16x32_bf16 v[44:47], v[134:137], v[212:215], v[44:47]
	v_mfma_f32_16x16x32_bf16 v[40:43], v[142:145], v[212:215], v[40:43]
	v_mfma_f32_16x16x32_bf16 v[28:31], v[134:137], v[220:223], v[28:31]
	v_mfma_f32_16x16x32_bf16 v[24:27], v[142:145], v[220:223], v[24:27]
	v_mfma_f32_16x16x32_bf16 v[12:15], v[134:137], v[228:231], v[12:15]
	v_mfma_f32_16x16x32_bf16 v[8:11], v[142:145], v[228:231], v[8:11]
	v_mfma_f32_16x16x32_bf16 v[52:55], v[146:149], v[188:191], v[52:55]
	v_mfma_f32_16x16x32_bf16 v[48:51], v[154:157], v[188:191], v[48:51]
	v_mfma_f32_16x16x32_bf16 v[36:39], v[146:149], v[208:211], v[36:39]
	v_mfma_f32_16x16x32_bf16 v[32:35], v[154:157], v[208:211], v[32:35]
	v_mfma_f32_16x16x32_bf16 v[20:23], v[146:149], v[216:219], v[20:23]
	v_mfma_f32_16x16x32_bf16 v[16:19], v[154:157], v[216:219], v[16:19]
	v_mfma_f32_16x16x32_bf16 v[4:7], v[146:149], v[224:227], v[4:7]
	v_mfma_f32_16x16x32_bf16 v[0:3], v[154:157], v[224:227], v[0:3]
	v_mfma_f32_16x16x32_bf16 v[52:55], v[150:153], v[192:195], v[52:55]
	v_mfma_f32_16x16x32_bf16 v[48:51], v[158:161], v[192:195], v[48:51]
	v_mfma_f32_16x16x32_bf16 v[36:39], v[150:153], v[212:215], v[36:39]
	v_mfma_f32_16x16x32_bf16 v[32:35], v[158:161], v[212:215], v[32:35]
	v_mfma_f32_16x16x32_bf16 v[20:23], v[150:153], v[220:223], v[20:23]
	v_mfma_f32_16x16x32_bf16 v[16:19], v[158:161], v[220:223], v[16:19]
	v_mfma_f32_16x16x32_bf16 v[4:7], v[150:153], v[228:231], v[4:7]
	v_mfma_f32_16x16x32_bf16 v[0:3], v[158:161], v[228:231], v[0:3]
	s_barrier
	s_setprio 0
	s_add_i32 s70, s70, 2
	s_add_u32 s6, s6, 0x100
	s_addc_u32 s7, s7, 0
	s_add_u32 s68, s68, 0x100
	s_addc_u32 s69, s69, 0
	s_cmp_gt_u32 s70, 13
	s_cbranch_scc0 .LBB0_159
	s_and_b64 vcc, exec, s[14:15]
	s_cbranch_vccz .LBB0_162
	s_barrier

; #define PG8_STAGE(bufoff, gbase, voff) do { _Pragma("unroll") for (int _i = 0; _i < 2; ++_i) \
;         __builtin_amdgcn_global_load_lds((const unsigned*)((const char*)(gbase) + (voff)[_i]), (PG8_LAS unsigned*)(lds + (bufoff) + ldsw + _i * 8192), 16, 0, 0); } while (0)
; #define PG8_LDA(dst, b, h) do { _Pragma("unroll") for (int m = 0; m < 4; ++m) _Pragma("unroll") for (int k = 0; k < 2; ++k) dst[m][k] = *(const PG8_LAS bf16x8*)(lds + PG8_SA(b, h) + aoff + m * 2048 + k * 1024); } while (0)
; #define PG8_LDB(dst, b, h) do { _Pragma("unroll") for (int n = 0; n < 2; ++n) _Pragma("unroll") for (int k = 0; k < 2; ++k) dst[n][k] = *(const PG8_LAS bf16x8*)(lds + PG8_SB(b, h) + boff + n * 2048 + k * 1024); } while (0)
; #define PG8_MMA(ai, bj, At, Bt) do { __builtin_amdgcn_s_setprio(1); _Pragma("unroll") for (int m = 0; m < 4; ++m) _Pragma("unroll") for (int n = 0; n < 2; ++n) _Pragma("unroll") for (int k = 0; k < 2; ++k) \
;         acc[ai][bj][m][n] = __builtin_amdgcn_mfma_f32_16x16x32_bf16(Bt[n][k], At[m][k], acc[ai][bj][m][n], 0, 0, 0); __builtin_amdgcn_s_setprio(0); } while (0)
; #define PG8_WAIT_V(n) asm volatile("s_waitcnt vmcnt(" #n ")" ::: "memory")
; #define PG8_WAIT_L(n) asm volatile("s_waitcnt lgkmcnt(" #n ")" ::: "memory")
; #define PG8_BAR __builtin_amdgcn_s_barrier()
; #define PG8_SCHED __builtin_amdgcn_sched_barrier(0)
; template <class Epi, class Sched, bool ALIGN_EPI = false, bool SP2 = false>
; __device__ __forceinline__ void gemm_phase(PG8_LAS unsigned char* lds, const Gemm g, const Sched& S, const Epi& E) {
;     ...
;             PG8_LDB(B0, 0, 0); PG8_LDB(B1, 0, 1); PG8_SCHED; PG8_LDA(At, 0, 0); PG8_STAGE(PG8_SA(1, 1), a1 + hstep, voffA);
;             PG8_WAIT_V(8); PG8_WAIT_L(0); PG8_BAR; PG8_MMA(0, 0, At, B0); PG8_MMA(0, 1, At, B1); PG8_BAR; PG8_SCHED;
;             PG8_LDA(At, 0, 1); PG8_STAGE(PG8_SB(0, 0), b2, voffB); PG8_STAGE(PG8_SB(0, 1), b2 + hstep, voffB); PG8_STAGE(PG8_SA(0, 0), a2, voffA);
.LBB0_383:
	s_add_i32 s73, s56, 2
	s_add_u32 s57, s44, s54
	s_addc_u32 s74, s45, s55
	s_add_u32 s75, s57, 0x100
	s_addc_u32 s57, s74, 0
	s_add_u32 s74, s47, s54
	s_addc_u32 s76, s49, s55
	s_add_i32 s77, 0, 0x10000
	s_cmp_eq_u32 s15, s56
	s_cselect_b32 s57, s5, s57
	s_cselect_b32 s56, s4, s75
	s_cselect_b32 s75, s43, s76
	s_cselect_b32 s74, s42, s74
	s_add_i32 s76, 0, 0x14000
	v_add_u32_e32 v146, s77, v209
	v_add_u32_e32 v188, s76, v209
	ds_read_b128 v[134:137], v146
	ds_read_b128 v[138:141], v146 offset:1024
	ds_read_b128 v[142:145], v146 offset:2048
	ds_read_b128 v[146:149], v146 offset:3072
	ds_read_b128 v[150:153], v188
	ds_read_b128 v[154:157], v188 offset:1024
	ds_read_b128 v[184:187], v188 offset:2048
	ds_read_b128 v[188:191], v188 offset:3072
	v_lshl_add_u64 v[200:201], v[130:131], 0, s[54:55]
	s_add_i32 m0, s58, 0xc000
	ds_read_b128 v[192:195], v211
	ds_read_b128 v[196:199], v211 offset:1024
	ds_read_b128 v[212:215], v211 offset:2048
	ds_read_b128 v[216:219], v211 offset:3072
	ds_read_b128 v[220:223], v211 offset:4096
	ds_read_b128 v[224:227], v211 offset:5120
	ds_read_b128 v[228:231], v211 offset:6144
	ds_read_b128 v[232:235], v211 offset:7168
	global_load_lds_dwordx4 v[200:201], off
	v_lshl_add_u64 v[200:201], v[132:133], 0, s[54:55]
	s_add_i32 m0, s58, 0xe000
	s_nop 0
	global_load_lds_dwordx4 v[200:201], off
	s_waitcnt vmcnt(8)
	s_waitcnt lgkmcnt(0)
	s_setprio 1
	s_barrier
	v_mfma_f32_16x16x32_bf16 v[126:129], v[134:137], v[192:195], v[126:129]
	v_mfma_f32_16x16x32_bf16 v[122:125], v[142:145], v[192:195], v[122:125]
	v_mfma_f32_16x16x32_bf16 v[110:113], v[134:137], v[212:215], v[110:113]
	v_mfma_f32_16x16x32_bf16 v[106:109], v[142:145], v[212:215], v[106:109]
	v_mfma_f32_16x16x32_bf16 v[94:97], v[134:137], v[220:223], v[94:97]
	v_mfma_f32_16x16x32_bf16 v[90:93], v[142:145], v[220:223], v[90:93]
	v_mfma_f32_16x16x32_bf16 v[76:79], v[134:137], v[228:231], v[76:79]
	v_mfma_f32_16x16x32_bf16 v[72:75], v[142:145], v[228:231], v[72:75]
	v_mfma_f32_16x16x32_bf16 v[126:129], v[138:141], v[196:199], v[126:129]
	v_mfma_f32_16x16x32_bf16 v[122:125], v[146:149], v[196:199], v[122:125]
	v_mfma_f32_16x16x32_bf16 v[110:113], v[138:141], v[216:219], v[110:113]
	v_mfma_f32_16x16x32_bf16 v[106:109], v[146:149], v[216:219], v[106:109]
	v_mfma_f32_16x16x32_bf16 v[94:97], v[138:141], v[224:227], v[94:97]
	v_mfma_f32_16x16x32_bf16 v[90:93], v[146:149], v[224:227], v[90:93]
	v_mfma_f32_16x16x32_bf16 v[76:79], v[138:141], v[232:235], v[76:79]
	v_mfma_f32_16x16x32_bf16 v[72:75], v[146:149], v[232:235], v[72:75]
	v_mfma_f32_16x16x32_bf16 v[118:121], v[150:153], v[192:195], v[118:121]
	v_mfma_f32_16x16x32_bf16 v[114:117], v[184:187], v[192:195], v[114:117]
	v_mfma_f32_16x16x32_bf16 v[102:105], v[150:153], v[212:215], v[102:105]
	v_mfma_f32_16x16x32_bf16 v[98:101], v[184:187], v[212:215], v[98:101]
	v_mfma_f32_16x16x32_bf16 v[86:89], v[150:153], v[220:223], v[86:89]
	v_mfma_f32_16x16x32_bf16 v[82:85], v[184:187], v[220:223], v[82:85]
	v_mfma_f32_16x16x32_bf16 v[68:71], v[150:153], v[228:231], v[68:71]
	v_mfma_f32_16x16x32_bf16 v[64:67], v[184:187], v[228:231], v[64:67]
	v_mfma_f32_16x16x32_bf16 v[118:121], v[154:157], v[196:199], v[118:121]
	v_mfma_f32_16x16x32_bf16 v[114:117], v[188:191], v[196:199], v[114:117]
	v_mfma_f32_16x16x32_bf16 v[102:105], v[154:157], v[216:219], v[102:105]
	v_mfma_f32_16x16x32_bf16 v[98:101], v[188:191], v[216:219], v[98:101]
	v_mfma_f32_16x16x32_bf16 v[86:89], v[154:157], v[224:227], v[86:89]
	v_mfma_f32_16x16x32_bf16 v[82:85], v[188:191], v[224:227], v[82:85]
	v_mfma_f32_16x16x32_bf16 v[68:71], v[154:157], v[232:235], v[68:71]
	v_mfma_f32_16x16x32_bf16 v[64:67], v[188:191], v[232:235], v[64:67]
	s_barrier
	s_setprio 0
	s_add_i32 s77, s77, s39
	v_lshl_add_u64 v[200:201], s[74:75], 0, v[176:177]
	s_mov_b32 m0, s77
	ds_read_b128 v[192:195], v211 offset:16384
	ds_read_b128 v[196:199], v211 offset:17408
	ds_read_b128 v[212:215], v211 offset:18432
	ds_read_b128 v[216:219], v211 offset:19456
	ds_read_b128 v[220:223], v211 offset:20480
	ds_read_b128 v[224:227], v211 offset:21504
	ds_read_b128 v[228:231], v211 offset:22528
	ds_read_b128 v[232:235], v211 offset:23552
	global_load_lds_dwordx4 v[200:201], off
	s_add_i32 m0, s77, 0x2000
	v_lshl_add_u64 v[236:237], s[74:75], 0, v[158:159]
	s_add_u32 s74, s74, s14
	s_addc_u32 s75, s75, 0
	s_add_i32 s76, s76, s39
	global_load_lds_dwordx4 v[236:237], off
	v_lshl_add_u64 v[238:239], s[74:75], 0, v[176:177]
	s_mov_b32 m0, s76
	v_lshl_add_u64 v[240:241], s[74:75], 0, v[158:159]
	global_load_lds_dwordx4 v[238:239], off
	s_add_i32 m0, s76, 0x2000
	v_lshl_add_u64 v[242:243], s[56:57], 0, v[178:179]
	global_load_lds_dwordx4 v[240:241], off
	s_mov_b32 m0, s58
	v_lshl_add_u64 v[244:245], s[56:57], 0, v[160:161]
	global_load_lds_dwordx4 v[242:243], off
	s_mov_b32 m0, s59
	s_nop 0
	global_load_lds_dwordx4 v[244:245], off
	s_waitcnt vmcnt(8)
	s_waitcnt lgkmcnt(0)
	s_setprio 1
	s_barrier
; #define PG8_STAGE(bufoff, gbase, voff) do { _Pragma("unroll") for (int _i = 0; _i < 2; ++_i) \
;         __builtin_amdgcn_global_load_lds((const unsigned*)((const char*)(gbase) + (voff)[_i]), (PG8_LAS unsigned*)(lds + (bufoff) + ldsw + _i * 8192), 16, 0, 0); } while (0)
; #define PG8_LDA(dst, b, h) do { _Pragma("unroll") for (int m = 0; m < 4; ++m) _Pragma("unroll") for (int k = 0; k < 2; ++k) dst[m][k] = *(const PG8_LAS bf16x8*)(lds + PG8_SA(b, h) + aoff + m * 2048 + k * 1024); } while (0)
; #define PG8_LDB(dst, b, h) do { _Pragma("unroll") for (int n = 0; n < 2; ++n) _Pragma("unroll") for (int k = 0; k < 2; ++k) dst[n][k] = *(const PG8_LAS bf16x8*)(lds + PG8_SB(b, h) + boff + n * 2048 + k * 1024); } while (0)
; #define PG8_MMA(ai, bj, At, Bt) do { __builtin_amdgcn_s_setprio(1); _Pragma("unroll") for (int m = 0; m < 4; ++m) _Pragma("unroll") for (int n = 0; n < 2; ++n) _Pragma("unroll") for (int k = 0; k < 2; ++k) \
;         acc[ai][bj][m][n] = __builtin_amdgcn_mfma_f32_16x16x32_bf16(Bt[n][k], At[m][k], acc[ai][bj][m][n], 0, 0, 0); __builtin_amdgcn_s_setprio(0); } while (0)
; #define PG8_WAIT_V(n) asm volatile("s_waitcnt vmcnt(" #n ")" ::: "memory")
; #define PG8_WAIT_L(n) asm volatile("s_waitcnt lgkmcnt(" #n ")" ::: "memory")
; #define PG8_BAR __builtin_amdgcn_s_barrier()
; #define PG8_SCHED __builtin_amdgcn_sched_barrier(0)
; template <class Epi, class Sched, bool ALIGN_EPI = false, bool SP2 = false>
; __device__ __forceinline__ void gemm_phase(PG8_LAS unsigned char* lds, const Gemm g, const Sched& S, const Epi& E) {
;     ...
;             PG8_LDA(At, 0, 1); PG8_STAGE(PG8_SB(0, 0), b2, voffB); PG8_STAGE(PG8_SB(0, 1), b2 + hstep, voffB); PG8_STAGE(PG8_SA(0, 0), a2, voffA);
;             PG8_WAIT_V(8); PG8_WAIT_L(0); PG8_BAR; PG8_MMA(1, 0, At, B0); PG8_MMA(1, 1, At, B1); PG8_BAR; PG8_SCHED;
;             PG8_LDB(B0, 1, 0); PG8_LDB(B1, 1, 1); PG8_SCHED; PG8_LDA(At, 1, 0); PG8_STAGE(PG8_SA(0, 1), a2 + hstep, voffA);
;             PG8_WAIT_V(8); PG8_WAIT_L(0); PG8_BAR; PG8_MMA(0, 0, At, B0); PG8_MMA(0, 1, At, B1); PG8_BAR; PG8_SCHED;
	v_mfma_f32_16x16x32_bf16 v[60:63], v[134:137], v[192:195], v[60:63]
	v_mfma_f32_16x16x32_bf16 v[56:59], v[142:145], v[192:195], v[56:59]
	v_mfma_f32_16x16x32_bf16 v[44:47], v[134:137], v[212:215], v[44:47]
	v_mfma_f32_16x16x32_bf16 v[40:43], v[142:145], v[212:215], v[40:43]
	v_mfma_f32_16x16x32_bf16 v[28:31], v[134:137], v[220:223], v[28:31]
	v_mfma_f32_16x16x32_bf16 v[24:27], v[142:145], v[220:223], v[24:27]
	v_mfma_f32_16x16x32_bf16 v[12:15], v[134:137], v[228:231], v[12:15]
	v_mfma_f32_16x16x32_bf16 v[8:11], v[142:145], v[228:231], v[8:11]
	v_mfma_f32_16x16x32_bf16 v[60:63], v[138:141], v[196:199], v[60:63]
	v_mfma_f32_16x16x32_bf16 v[56:59], v[146:149], v[196:199], v[56:59]
	v_mfma_f32_16x16x32_bf16 v[44:47], v[138:141], v[216:219], v[44:47]
	v_mfma_f32_16x16x32_bf16 v[40:43], v[146:149], v[216:219], v[40:43]
	v_mfma_f32_16x16x32_bf16 v[28:31], v[138:141], v[224:227], v[28:31]
	v_mfma_f32_16x16x32_bf16 v[24:27], v[146:149], v[224:227], v[24:27]
	v_mfma_f32_16x16x32_bf16 v[12:15], v[138:141], v[232:235], v[12:15]
	v_mfma_f32_16x16x32_bf16 v[8:11], v[146:149], v[232:235], v[8:11]
	v_mfma_f32_16x16x32_bf16 v[52:55], v[150:153], v[192:195], v[52:55]
	v_mfma_f32_16x16x32_bf16 v[48:51], v[184:187], v[192:195], v[48:51]
	v_mfma_f32_16x16x32_bf16 v[36:39], v[150:153], v[212:215], v[36:39]
	v_mfma_f32_16x16x32_bf16 v[32:35], v[184:187], v[212:215], v[32:35]
	v_mfma_f32_16x16x32_bf16 v[20:23], v[150:153], v[220:223], v[20:23]
	v_mfma_f32_16x16x32_bf16 v[16:19], v[184:187], v[220:223], v[16:19]
	v_mfma_f32_16x16x32_bf16 v[4:7], v[150:153], v[228:231], v[4:7]
	v_mfma_f32_16x16x32_bf16 v[0:3], v[184:187], v[228:231], v[0:3]
	v_mfma_f32_16x16x32_bf16 v[52:55], v[154:157], v[196:199], v[52:55]
	v_mfma_f32_16x16x32_bf16 v[48:51], v[188:191], v[196:199], v[48:51]
	v_mfma_f32_16x16x32_bf16 v[36:39], v[154:157], v[216:219], v[36:39]
	v_mfma_f32_16x16x32_bf16 v[32:35], v[188:191], v[216:219], v[32:35]
	v_mfma_f32_16x16x32_bf16 v[20:23], v[154:157], v[224:227], v[20:23]
	v_mfma_f32_16x16x32_bf16 v[16:19], v[188:191], v[224:227], v[16:19]
	v_mfma_f32_16x16x32_bf16 v[4:7], v[154:157], v[232:235], v[4:7]
	v_mfma_f32_16x16x32_bf16 v[0:3], v[188:191], v[232:235], v[0:3]
	s_barrier
	s_setprio 0
	s_add_i32 s74, 0, 0x18000
	s_add_i32 s75, 0, 0x1c000
	v_add_u32_e32 v146, s74, v209
	v_add_u32_e32 v188, s75, v209
	ds_read_b128 v[134:137], v146
	ds_read_b128 v[138:141], v146 offset:1024
	ds_read_b128 v[142:145], v146 offset:2048
	ds_read_b128 v[146:149], v146 offset:3072
	ds_read_b128 v[150:153], v188
	ds_read_b128 v[154:157], v188 offset:1024
	ds_read_b128 v[184:187], v188 offset:2048
	ds_read_b128 v[188:191], v188 offset:3072
	s_add_u32 s56, s56, s14
	s_addc_u32 s57, s57, 0
	s_mov_b32 m0, s60
	v_lshl_add_u64 v[246:247], s[56:57], 0, v[178:179]
	ds_read_b128 v[192:195], v211 offset:32768
	ds_read_b128 v[196:199], v211 offset:33792
	ds_read_b128 v[212:215], v211 offset:34816
	ds_read_b128 v[216:219], v211 offset:35840
	ds_read_b128 v[220:223], v211 offset:36864
	ds_read_b128 v[224:227], v211 offset:37888
	ds_read_b128 v[228:231], v211 offset:38912
	ds_read_b128 v[232:235], v211 offset:39936
	global_load_lds_dwordx4 v[246:247], off
	v_lshl_add_u64 v[246:247], s[56:57], 0, v[160:161]
	s_mov_b32 m0, s61
	s_nop 0
	global_load_lds_dwordx4 v[246:247], off
	s_waitcnt vmcnt(8)
	s_waitcnt lgkmcnt(0)
	s_setprio 1
	s_barrier
	v_mfma_f32_16x16x32_bf16 v[126:129], v[134:137], v[192:195], v[126:129]
	v_mfma_f32_16x16x32_bf16 v[122:125], v[142:145], v[192:195], v[122:125]
	v_mfma_f32_16x16x32_bf16 v[110:113], v[134:137], v[212:215], v[110:113]
	v_mfma_f32_16x16x32_bf16 v[106:109], v[142:145], v[212:215], v[106:109]
	v_mfma_f32_16x16x32_bf16 v[94:97], v[134:137], v[220:223], v[94:97]
	v_mfma_f32_16x16x32_bf16 v[90:93], v[142:145], v[220:223], v[90:93]
	v_mfma_f32_16x16x32_bf16 v[76:79], v[134:137], v[228:231], v[76:79]
	v_mfma_f32_16x16x32_bf16 v[72:75], v[142:145], v[228:231], v[72:75]
	v_mfma_f32_16x16x32_bf16 v[126:129], v[138:141], v[196:199], v[126:129]
	v_mfma_f32_16x16x32_bf16 v[122:125], v[146:149], v[196:199], v[122:125]
	v_mfma_f32_16x16x32_bf16 v[110:113], v[138:141], v[216:219], v[110:113]
	v_mfma_f32_16x16x32_bf16 v[106:109], v[146:149], v[216:219], v[106:109]
	v_mfma_f32_16x16x32_bf16 v[94:97], v[138:141], v[224:227], v[94:97]
	v_mfma_f32_16x16x32_bf16 v[90:93], v[146:149], v[224:227], v[90:93]
	v_mfma_f32_16x16x32_bf16 v[76:79], v[138:141], v[232:235], v[76:79]
	v_mfma_f32_16x16x32_bf16 v[72:75], v[146:149], v[232:235], v[72:75]
	v_mfma_f32_16x16x32_bf16 v[118:121], v[150:153], v[192:195], v[118:121]
	v_mfma_f32_16x16x32_bf16 v[114:117], v[184:187], v[192:195], v[114:117]
	v_mfma_f32_16x16x32_bf16 v[102:105], v[150:153], v[212:215], v[102:105]
	v_mfma_f32_16x16x32_bf16 v[98:101], v[184:187], v[212:215], v[98:101]
	v_mfma_f32_16x16x32_bf16 v[86:89], v[150:153], v[220:223], v[86:89]
	v_mfma_f32_16x16x32_bf16 v[82:85], v[184:187], v[220:223], v[82:85]
	v_mfma_f32_16x16x32_bf16 v[68:71], v[150:153], v[228:231], v[68:71]
	v_mfma_f32_16x16x32_bf16 v[64:67], v[184:187], v[228:231], v[64:67]
	v_mfma_f32_16x16x32_bf16 v[118:121], v[154:157], v[196:199], v[118:121]
	v_mfma_f32_16x16x32_bf16 v[114:117], v[188:191], v[196:199], v[114:117]
	v_mfma_f32_16x16x32_bf16 v[102:105], v[154:157], v[216:219], v[102:105]
	v_mfma_f32_16x16x32_bf16 v[98:101], v[188:191], v[216:219], v[98:101]
	v_mfma_f32_16x16x32_bf16 v[86:89], v[154:157], v[224:227], v[86:89]
	v_mfma_f32_16x16x32_bf16 v[82:85], v[188:191], v[224:227], v[82:85]
	v_mfma_f32_16x16x32_bf16 v[68:71], v[154:157], v[232:235], v[68:71]
	v_mfma_f32_16x16x32_bf16 v[64:67], v[188:191], v[232:235], v[64:67]
	s_barrier
; #define PG8_STAGE(bufoff, gbase, voff) do { _Pragma("unroll") for (int _i = 0; _i < 2; ++_i) \
;         __builtin_amdgcn_global_load_lds((const unsigned*)((const char*)(gbase) + (voff)[_i]), (PG8_LAS unsigned*)(lds + (bufoff) + ldsw + _i * 8192), 16, 0, 0); } while (0)
; #define PG8_LDA(dst, b, h) do { _Pragma("unroll") for (int m = 0; m < 4; ++m) _Pragma("unroll") for (int k = 0; k < 2; ++k) dst[m][k] = *(const PG8_LAS bf16x8*)(lds + PG8_SA(b, h) + aoff + m * 2048 + k * 1024); } while (0)
; #define PG8_MMA(ai, bj, At, Bt) do { __builtin_amdgcn_s_setprio(1); _Pragma("unroll") for (int m = 0; m < 4; ++m) _Pragma("unroll") for (int n = 0; n < 2; ++n) _Pragma("unroll") for (int k = 0; k < 2; ++k) \
;         acc[ai][bj][m][n] = __builtin_amdgcn_mfma_f32_16x16x32_bf16(Bt[n][k], At[m][k], acc[ai][bj][m][n], 0, 0, 0); __builtin_amdgcn_s_setprio(0); } while (0)
; #define PG8_WAIT_V(n) asm volatile("s_waitcnt vmcnt(" #n ")" ::: "memory")
; #define PG8_WAIT_L(n) asm volatile("s_waitcnt lgkmcnt(" #n ")" ::: "memory")
; #define PG8_BAR __builtin_amdgcn_s_barrier()
; #define PG8_SCHED __builtin_amdgcn_sched_barrier(0)
; template <class Epi, class Sched, bool ALIGN_EPI = false, bool SP2 = false>
; __device__ __forceinline__ void gemm_phase(PG8_LAS unsigned char* lds, const Gemm g, const Sched& S, const Epi& E) {
;     ...
;         for (int t = 0; t < nt; t += 2) {
;     ...
;             PG8_LDA(At, 1, 1); PG8_STAGE(PG8_SB(1, 0), b3, voffB); PG8_STAGE(PG8_SB(1, 1), b3 + hstep, voffB); PG8_STAGE(PG8_SA(1, 0), a3, voffA);
;             PG8_WAIT_V(8); PG8_WAIT_L(0); PG8_BAR; PG8_MMA(1, 0, At, B0); PG8_MMA(1, 1, At, B1); PG8_BAR; PG8_SCHED;
	s_setprio 0
	s_add_i32 s56, s74, s39
	v_lshl_add_u64 v[200:201], v[200:201], 0, s[40:41]
	s_mov_b32 m0, s56
	ds_read_b128 v[192:195], v211 offset:49152
	ds_read_b128 v[196:199], v211 offset:50176
	ds_read_b128 v[212:215], v211 offset:51200
	ds_read_b128 v[216:219], v211 offset:52224
	ds_read_b128 v[220:223], v211 offset:53248
	ds_read_b128 v[224:227], v211 offset:54272
	ds_read_b128 v[228:231], v211 offset:55296
	ds_read_b128 v[232:235], v211 offset:56320
	global_load_lds_dwordx4 v[200:201], off
	v_lshl_add_u64 v[200:201], v[236:237], 0, s[40:41]
	s_add_i32 m0, s56, 0x2000
	s_add_i32 s56, s75, s39
	global_load_lds_dwordx4 v[200:201], off
	v_lshl_add_u64 v[200:201], v[238:239], 0, s[40:41]
	s_mov_b32 m0, s56
	s_nop 0
	global_load_lds_dwordx4 v[200:201], off
	v_lshl_add_u64 v[200:201], v[240:241], 0, s[40:41]
	s_add_i32 m0, s56, 0x2000
	s_nop 0
	global_load_lds_dwordx4 v[200:201], off
	v_lshl_add_u64 v[200:201], v[242:243], 0, s[40:41]
	s_mov_b32 m0, s66
	s_nop 0
	global_load_lds_dwordx4 v[200:201], off
	v_lshl_add_u64 v[200:201], v[244:245], 0, s[40:41]
	s_mov_b32 m0, s67
	s_nop 0
	global_load_lds_dwordx4 v[200:201], off
	s_waitcnt vmcnt(8)
	s_waitcnt lgkmcnt(0)
	s_setprio 1
	s_barrier
	v_mfma_f32_16x16x32_bf16 v[60:63], v[134:137], v[192:195], v[60:63]
	v_mfma_f32_16x16x32_bf16 v[56:59], v[142:145], v[192:195], v[56:59]
	v_mfma_f32_16x16x32_bf16 v[44:47], v[134:137], v[212:215], v[44:47]
	v_mfma_f32_16x16x32_bf16 v[40:43], v[142:145], v[212:215], v[40:43]
	v_mfma_f32_16x16x32_bf16 v[28:31], v[134:137], v[220:223], v[28:31]
	v_mfma_f32_16x16x32_bf16 v[24:27], v[142:145], v[220:223], v[24:27]
	v_mfma_f32_16x16x32_bf16 v[12:15], v[134:137], v[228:231], v[12:15]
	v_mfma_f32_16x16x32_bf16 v[8:11], v[142:145], v[228:231], v[8:11]
	v_mfma_f32_16x16x32_bf16 v[60:63], v[138:141], v[196:199], v[60:63]
	v_mfma_f32_16x16x32_bf16 v[56:59], v[146:149], v[196:199], v[56:59]
	v_mfma_f32_16x16x32_bf16 v[44:47], v[138:141], v[216:219], v[44:47]
	v_mfma_f32_16x16x32_bf16 v[40:43], v[146:149], v[216:219], v[40:43]
	v_mfma_f32_16x16x32_bf16 v[28:31], v[138:141], v[224:227], v[28:31]
	v_mfma_f32_16x16x32_bf16 v[24:27], v[146:149], v[224:227], v[24:27]
	v_mfma_f32_16x16x32_bf16 v[12:15], v[138:141], v[232:235], v[12:15]
	v_mfma_f32_16x16x32_bf16 v[8:11], v[146:149], v[232:235], v[8:11]
	v_mfma_f32_16x16x32_bf16 v[52:55], v[150:153], v[192:195], v[52:55]
	v_mfma_f32_16x16x32_bf16 v[48:51], v[184:187], v[192:195], v[48:51]
	v_mfma_f32_16x16x32_bf16 v[36:39], v[150:153], v[212:215], v[36:39]
	v_mfma_f32_16x16x32_bf16 v[32:35], v[184:187], v[212:215], v[32:35]
	v_mfma_f32_16x16x32_bf16 v[20:23], v[150:153], v[220:223], v[20:23]
	v_mfma_f32_16x16x32_bf16 v[16:19], v[184:187], v[220:223], v[16:19]
	v_mfma_f32_16x16x32_bf16 v[4:7], v[150:153], v[228:231], v[4:7]
	v_mfma_f32_16x16x32_bf16 v[0:3], v[184:187], v[228:231], v[0:3]
	v_mfma_f32_16x16x32_bf16 v[52:55], v[154:157], v[196:199], v[52:55]
	v_mfma_f32_16x16x32_bf16 v[48:51], v[188:191], v[196:199], v[48:51]
	v_mfma_f32_16x16x32_bf16 v[36:39], v[154:157], v[216:219], v[36:39]
	v_mfma_f32_16x16x32_bf16 v[32:35], v[188:191], v[216:219], v[32:35]
	v_mfma_f32_16x16x32_bf16 v[20:23], v[154:157], v[224:227], v[20:23]
	v_mfma_f32_16x16x32_bf16 v[16:19], v[188:191], v[224:227], v[16:19]
	v_mfma_f32_16x16x32_bf16 v[4:7], v[154:157], v[232:235], v[4:7]
	v_mfma_f32_16x16x32_bf16 v[0:3], v[188:191], v[232:235], v[0:3]
	s_barrier
	s_setprio 0
	s_add_u32 s54, s54, 0x100
	s_addc_u32 s55, s55, 0
	s_cmp_ge_u32 s73, s63
	s_mov_b32 s56, s73
	s_cbranch_scc1 .LBB0_386
